# ff2 epilogue: batch residual loads 8 at a time per 16-row group instead of 32 serialized load-store round trips
# speedup vs baseline: 1.0145x; 1.0145x over previous
; template <int MODE, int HALF>
; __device__ void gemm_phase(const P& p, int layer, char* smem) {
;     ...
;       for (int mi = 0; mi < 4; ++mi) {
;         float sq[4] = {0.f, 0.f, 0.f, 0.f};
; #pragma unroll
;         for (int hc = 0; hc < 2; ++hc) {
; #pragma unroll
;           for (int j = 0; j < 4; ++j)
; #pragma unroll
;             for (int n4 = 0; n4 < 4; ++n4) pf[(lqe * 4 + j) * 68 + n4 * 16 + lre] = acc[mi][hc * 4 + n4][j];
;           asm volatile("" ::: "memory");
; #pragma unroll
;           for (int it = 0; it < 4; ++it) {
;             int idx = it * 64 + lane, r = idx >> 4, ch = idx & 15;
;             float4 a4 = *(const float4*)(pf + r * 68 + ch * 4);
;             size_t grow = row0 + wm * 64 + mi * 16 + r;
;             int col = nt * 128 + hc * 64 + ch * 4;
;             float* xo = p.out + grow * 1024 + col;
;             float4 xr = (MODE == 1 && layer == 0) ? *(const float4*)(xin_row(p, grow) + col) : *(const float4*)xo;
;             float4 xn = make_float4(xr.x + a4.x, xr.y + a4.y, xr.z + a4.z, xr.w + a4.w);
;             *(float4*)xo = xn;
;             if (WRITE_XB) {
;               uint2 b2; b2.x = pack2(xn.x, xn.y); b2.y = pack2(xn.z, xn.w);
;               *(uint2*)((bf16_t*)(p.ws + OFF_XB) + grow * 1024 + col) = b2;
;               sq[it] += xn.x * xn.x + xn.y * xn.y + xn.z * xn.z + xn.w * xn.w;
;             }
.LBB0_116:
	s_ashr_i32 s2, s11, 31
	s_lshr_b32 s2, s2, 30
	s_add_i32 s13, s11, s2
	s_ashr_i32 s2, s13, 2
	s_and_b32 s13, s13, 0xfffffc
	s_sub_i32 s13, s11, s13
	s_ashr_i32 s3, s2, 31
	v_mov_b32_e32 v174, v152
	v_mov_b32_e32 v172, v153
	v_lshl_or_b32 v184, s13, 8, v171
	s_movk_i32 s13, 0x440
	s_lshl_b64 s[14:15], s[2:3], 7
	v_ashrrev_i32_e32 v185, 31, v184
	v_lshlrev_b32_e32 v175, 2, v172
	v_mul_lo_u32 v181, v174, s13
	v_lshl_add_u64 v[172:173], s[14:15], 0, v[162:163]
	v_add3_u32 v175, v169, v175, v181
	v_add_u32_e32 v183, 0xc000, v175
	v_or_b32_e32 v186, v172, v152
	v_mov_b32_e32 v187, v173
	ds_write2_b32 v183, v148, v144 offset1:16
	ds_write2_b32 v183, v140, v136 offset0:32 offset1:48
	ds_write2_b32 v183, v149, v145 offset0:68 offset1:84
	ds_write2_b32 v183, v141, v137 offset0:100 offset1:116
	ds_write2_b32 v183, v150, v146 offset0:136 offset1:152
	ds_write2_b32 v183, v142, v138 offset0:168 offset1:184
	ds_write2_b32 v183, v151, v147 offset0:204 offset1:220
	ds_write2_b32 v183, v143, v139 offset0:236 offset1:252
	v_lshlrev_b64 v[136:137], 12, v[186:187]
	v_lshl_add_u64 v[136:137], s[56:57], 0, v[136:137]
	v_lshlrev_b64 v[150:151], 2, v[184:185]
	v_lshl_add_u64 v[192:193], v[136:137], 0, v[150:151]
	v_mov_b32_e32 v216, v192
	v_mov_b32_e32 v217, v193
	v_mov_b32_e32 v218, 0
	v_mov_b32_e32 v219, 0
	v_lshl_add_u64 v[218:219], v[216:217], 0, v[218:219]
	global_load_dwordx4 v[0:3], v[218:219], off
	v_mov_b32_e32 v218, 0x4000
	v_mov_b32_e32 v219, 0
	v_lshl_add_u64 v[218:219], v[216:217], 0, v[218:219]
	global_load_dwordx4 v[4:7], v[218:219], off
	v_mov_b32_e32 v218, 0x8000
	v_mov_b32_e32 v219, 0
	v_lshl_add_u64 v[218:219], v[216:217], 0, v[218:219]
	global_load_dwordx4 v[8:11], v[218:219], off
	v_mov_b32_e32 v218, 0xc000
	v_mov_b32_e32 v219, 0
	v_lshl_add_u64 v[218:219], v[216:217], 0, v[218:219]
	global_load_dwordx4 v[12:15], v[218:219], off
	v_mov_b32_e32 v218, 0
	v_mov_b32_e32 v219, 0
	v_lshl_add_u64 v[218:219], v[216:217], 0, v[218:219]
	global_load_dwordx4 v[16:19], v[218:219], off offset:256
	v_mov_b32_e32 v218, 0x4000
	v_mov_b32_e32 v219, 0
	v_lshl_add_u64 v[218:219], v[216:217], 0, v[218:219]
	global_load_dwordx4 v[20:23], v[218:219], off offset:256
	v_mov_b32_e32 v218, 0x8000
	v_mov_b32_e32 v219, 0
	v_lshl_add_u64 v[218:219], v[216:217], 0, v[218:219]
	global_load_dwordx4 v[208:211], v[218:219], off offset:256
	v_mov_b32_e32 v218, 0xc000
	v_mov_b32_e32 v219, 0
	v_lshl_add_u64 v[218:219], v[216:217], 0, v[218:219]
	global_load_dwordx4 v[212:215], v[218:219], off offset:256
	s_waitcnt vmcnt(7)
	s_nop 1
	v_mov_b32_e32 v136, v0
	v_mov_b32_e32 v137, v1
	v_mov_b32_e32 v138, v2
	v_mov_b32_e32 v139, v3
	ds_read_b128 v[140:143], v180 offset:49152
	ds_read_b128 v[144:147], v180 offset:50240
	v_or_b32_e32 v188, v172, v166
	v_mov_b32_e32 v189, v173
	v_lshlrev_b64 v[148:149], 1, v[184:185]
	v_lshlrev_b64 v[184:185], 11, v[186:187]
	v_lshlrev_b64 v[186:187], 12, v[188:189]
	v_lshl_add_u64 v[184:185], s[50:51], 0, v[184:185]
	v_lshl_add_u64 v[186:187], s[56:57], 0, v[186:187]
	v_lshl_add_u64 v[194:195], v[184:185], 0, v[148:149]
	v_lshl_add_u64 v[196:197], v[186:187], 0, v[150:151]
	v_or_b32_e32 v198, v172, v168
	v_mov_b32_e32 v199, v173
	v_or_b32_e32 v204, v172, v170
	v_mov_b32_e32 v205, v173
	v_lshlrev_b64 v[206:207], 12, v[204:205]
	v_lshl_add_u64 v[206:207], s[56:57], 0, v[206:207]
	v_lshl_add_u64 v[206:207], v[206:207], 0, v[150:151]
	v_lshlrev_b64 v[204:205], 11, v[204:205]
	v_lshl_add_u64 v[204:205], s[50:51], 0, v[204:205]
	v_lshl_add_u64 v[204:205], v[204:205], 0, v[148:149]
	v_xor_b32_e32 v181, 4, v221
	v_xor_b32_e32 v182, 8, v221
	s_lshl_b64 s[2:3], s[2:3], 9
	s_waitcnt lgkmcnt(1)
	v_pk_add_f32 v[184:185], v[140:141], v[136:137]
	v_pk_add_f32 v[186:187], v[142:143], v[138:139]
	v_cvt_pk_bf16_f32 v136, v184, v185
	v_cvt_pk_bf16_f32 v137, v186, v187
	global_store_dwordx4 v[192:193], v[184:187], off
	global_store_dwordx2 v[194:195], v[136:137], off
	s_waitcnt vmcnt(8)
	s_nop 1
	v_mov_b32_e32 v136, v4
	v_mov_b32_e32 v137, v5
	v_mov_b32_e32 v138, v6
	v_mov_b32_e32 v139, v7
	v_lshlrev_b64 v[140:141], 11, v[188:189]
	v_lshlrev_b64 v[142:143], 12, v[198:199]
	v_lshl_add_u64 v[140:141], s[50:51], 0, v[140:141]
	v_lshl_add_u64 v[142:143], s[56:57], 0, v[142:143]
	v_lshl_add_u64 v[200:201], v[140:141], 0, v[148:149]
	v_lshl_add_u64 v[202:203], v[142:143], 0, v[150:151]
	v_lshlrev_b64 v[198:199], 11, v[198:199]
	v_lshl_add_u64 v[198:199], s[50:51], 0, v[198:199]
	v_lshl_add_u64 v[198:199], v[198:199], 0, v[148:149]
	s_waitcnt lgkmcnt(0)
	v_pk_add_f32 v[136:137], v[144:145], v[136:137]
	v_pk_add_f32 v[138:139], v[146:147], v[138:139]
	v_cvt_pk_bf16_f32 v140, v136, v137
	v_cvt_pk_bf16_f32 v141, v138, v139
	global_store_dwordx4 v[196:197], v[136:139], off
	global_store_dwordx2 v[200:201], v[140:141], off
	s_waitcnt vmcnt(9)
	s_nop 1
	v_mov_b32_e32 v140, v8
	v_mov_b32_e32 v141, v9
	v_mov_b32_e32 v142, v10
	v_mov_b32_e32 v143, v11
	ds_read_b128 v[144:147], v180 offset:51328
	ds_read_b128 v[188:191], v180 offset:52416
	s_waitcnt lgkmcnt(1)
	v_pk_add_f32 v[144:145], v[144:145], v[140:141]
	v_pk_add_f32 v[146:147], v[146:147], v[142:143]
	v_cvt_pk_bf16_f32 v140, v144, v145
	v_cvt_pk_bf16_f32 v141, v146, v147
	global_store_dwordx4 v[202:203], v[144:147], off
	global_store_dwordx2 v[198:199], v[140:141], off
	s_waitcnt vmcnt(10)
	s_nop 1
	v_mov_b32_e32 v140, v12
	v_mov_b32_e32 v141, v13
	v_mov_b32_e32 v142, v14
	v_mov_b32_e32 v143, v15
	s_waitcnt lgkmcnt(0)
; template <int MODE, int HALF>
; __device__ void gemm_phase(const P& p, int layer, char* smem) {
;     ...
;         for (int hc = 0; hc < 2; ++hc) {
; #pragma unroll
;           for (int j = 0; j < 4; ++j)
; #pragma unroll
;             for (int n4 = 0; n4 < 4; ++n4) pf[(lqe * 4 + j) * 68 + n4 * 16 + lre] = acc[mi][hc * 4 + n4][j];
;           asm volatile("" ::: "memory");
; #pragma unroll
;           for (int it = 0; it < 4; ++it) {
;             int idx = it * 64 + lane, r = idx >> 4, ch = idx & 15;
;             float4 a4 = *(const float4*)(pf + r * 68 + ch * 4);
;             size_t grow = row0 + wm * 64 + mi * 16 + r;
;             int col = nt * 128 + hc * 64 + ch * 4;
;             float* xo = p.out + grow * 1024 + col;
;             float4 xr = (MODE == 1 && layer == 0) ? *(const float4*)(xin_row(p, grow) + col) : *(const float4*)xo;
;             float4 xn = make_float4(xr.x + a4.x, xr.y + a4.y, xr.z + a4.z, xr.w + a4.w);
;             *(float4*)xo = xn;
;             if (WRITE_XB) {
;               uint2 b2; b2.x = pack2(xn.x, xn.y); b2.y = pack2(xn.z, xn.w);
;               *(uint2*)((bf16_t*)(p.ws + OFF_XB) + grow * 1024 + col) = b2;
;               sq[it] += xn.x * xn.x + xn.y * xn.y + xn.z * xn.z + xn.w * xn.w;
;             }
;           }
;           asm volatile("" ::: "memory");
;         }
;         if (WRITE_XB) {
; #pragma unroll
;           for (int it = 0; it < 4; ++it) {
;             float s = sq[it];
;             s += __shfl_xor(s, 1); s += __shfl_xor(s, 2); s += __shfl_xor(s, 4); s += __shfl_xor(s, 8);
;             if ((lane & 15) == 0) atomicAdd(((MODE == 1) ? RSa : RSb) + row0 + wm * 64 + mi * 16 + it * 4 + lqe, s);
;           }
	v_pk_add_f32 v[140:141], v[188:189], v[140:141]
	v_pk_add_f32 v[142:143], v[190:191], v[142:143]
	v_cvt_pk_bf16_f32 v188, v140, v141
	v_cvt_pk_bf16_f32 v189, v142, v143
	global_store_dwordx4 v[206:207], v[140:143], off
	global_store_dwordx2 v[204:205], v[188:189], off
	ds_write2_b32 v183, v132, v128 offset1:16
	ds_write2_b32 v183, v124, v120 offset0:32 offset1:48
	ds_write2_b32 v183, v133, v129 offset0:68 offset1:84
	ds_write2_b32 v183, v125, v121 offset0:100 offset1:116
	ds_write2_b32 v183, v134, v130 offset0:136 offset1:152
	ds_write2_b32 v183, v126, v122 offset0:168 offset1:184
	ds_write2_b32 v183, v135, v131 offset0:204 offset1:220
	ds_write2_b32 v183, v127, v123 offset0:236 offset1:252
	s_waitcnt vmcnt(11)
	s_nop 1
	v_mov_b32_e32 v120, v16
	v_mov_b32_e32 v121, v17
	v_mov_b32_e32 v122, v18
	v_mov_b32_e32 v123, v19
	ds_read_b128 v[124:127], v180 offset:49152
	ds_read_b128 v[128:131], v180 offset:50240
	v_and_b32_e32 v133, 64, v221
	v_xor_b32_e32 v132, 1, v221
	v_xor_b32_e32 v135, 2, v221
	s_waitcnt lgkmcnt(1)
	v_pk_add_f32 v[188:189], v[124:125], v[120:121]
	v_pk_add_f32 v[190:191], v[126:127], v[122:123]
	v_cvt_pk_bf16_f32 v120, v188, v189
	v_cvt_pk_bf16_f32 v121, v190, v191
	global_store_dwordx4 v[192:193], v[188:191], off offset:256
	global_store_dwordx2 v[194:195], v[120:121], off offset:128
	s_waitcnt vmcnt(12)
	s_nop 1
	v_mov_b32_e32 v120, v20
	v_mov_b32_e32 v121, v21
	v_mov_b32_e32 v122, v22
	v_mov_b32_e32 v123, v23
	s_waitcnt lgkmcnt(0)
	v_pk_add_f32 v[120:121], v[128:129], v[120:121]
	v_pk_add_f32 v[122:123], v[130:131], v[122:123]
	v_cvt_pk_bf16_f32 v124, v120, v121
	v_cvt_pk_bf16_f32 v125, v122, v123
	global_store_dwordx4 v[196:197], v[120:123], off offset:256
	global_store_dwordx2 v[200:201], v[124:125], off offset:128
	s_waitcnt vmcnt(13)
	s_nop 1
	v_mov_b32_e32 v124, v208
	v_mov_b32_e32 v125, v209
	v_mov_b32_e32 v126, v210
	v_mov_b32_e32 v127, v211
	ds_read_b128 v[128:131], v180 offset:51328
	ds_read_b128 v[192:195], v180 offset:52416
	v_add_u32_e32 v196, 64, v133
	v_cmp_lt_i32_e32 vcc, v132, v196
	s_waitcnt lgkmcnt(1)
	v_pk_add_f32 v[124:125], v[128:129], v[124:125]
	v_pk_add_f32 v[126:127], v[130:131], v[126:127]
	v_cvt_pk_bf16_f32 v128, v124, v125
	v_cvt_pk_bf16_f32 v129, v126, v127
	global_store_dwordx4 v[202:203], v[124:127], off offset:256
	global_store_dwordx2 v[198:199], v[128:129], off offset:128
	s_waitcnt vmcnt(14)
	s_nop 1
	v_mov_b32_e32 v128, v212
	v_mov_b32_e32 v129, v213
	v_mov_b32_e32 v130, v214
	v_mov_b32_e32 v131, v215
	v_mov_b32_e32 v218, 0x10000
	v_mov_b32_e32 v219, 0
	v_lshl_add_u64 v[218:219], v[216:217], 0, v[218:219]
	global_load_dwordx4 v[0:3], v[218:219], off
	v_mov_b32_e32 v218, 0x14000
	v_mov_b32_e32 v219, 0
	v_lshl_add_u64 v[218:219], v[216:217], 0, v[218:219]
	global_load_dwordx4 v[4:7], v[218:219], off
	v_mov_b32_e32 v218, 0x18000
	v_mov_b32_e32 v219, 0
	v_lshl_add_u64 v[218:219], v[216:217], 0, v[218:219]
	global_load_dwordx4 v[8:11], v[218:219], off
	v_mov_b32_e32 v218, 0x1c000
	v_mov_b32_e32 v219, 0
	v_lshl_add_u64 v[218:219], v[216:217], 0, v[218:219]
	global_load_dwordx4 v[12:15], v[218:219], off
	v_mov_b32_e32 v218, 0x10000
	v_mov_b32_e32 v219, 0
	v_lshl_add_u64 v[218:219], v[216:217], 0, v[218:219]
	global_load_dwordx4 v[16:19], v[218:219], off offset:256
	v_mov_b32_e32 v218, 0x14000
	v_mov_b32_e32 v219, 0
	v_lshl_add_u64 v[218:219], v[216:217], 0, v[218:219]
	global_load_dwordx4 v[20:23], v[218:219], off offset:256
	v_mov_b32_e32 v218, 0x18000
	v_mov_b32_e32 v219, 0
	v_lshl_add_u64 v[218:219], v[216:217], 0, v[218:219]
	global_load_dwordx4 v[208:211], v[218:219], off offset:256
	v_mov_b32_e32 v218, 0x1c000
	v_mov_b32_e32 v219, 0
	v_lshl_add_u64 v[218:219], v[216:217], 0, v[218:219]
	global_load_dwordx4 v[212:215], v[218:219], off offset:256
	v_cndmask_b32_e32 v132, v221, v132, vcc
	v_lshlrev_b32_e32 v134, 2, v132
	v_pk_mul_f32 v[132:133], v[184:185], v[184:185]
	v_pk_mul_f32 v[184:185], v[186:187], v[186:187]
	v_add_f32_e32 v132, v132, v133
	v_add_f32_e32 v132, v132, v184
	v_add_f32_e32 v175, v132, v185
	v_pk_mul_f32 v[132:133], v[188:189], v[188:189]
	v_pk_mul_f32 v[184:185], v[190:191], v[190:191]
	v_add_f32_e32 v132, v132, v133
	v_add_f32_e32 v132, v132, v184
	v_add_f32_e32 v132, v132, v185
	v_add_f32_e32 v132, v175, v132
	ds_bpermute_b32 v133, v134, v132
	v_cmp_lt_i32_e32 vcc, v135, v196
	v_ashrrev_i32_e32 v175, 31, v174
	s_waitcnt lgkmcnt(0)
	v_add_f32_e32 v132, v132, v133
	v_cndmask_b32_e32 v135, v221, v135, vcc
	v_lshlrev_b32_e32 v135, 2, v135
	ds_bpermute_b32 v133, v135, v132
	v_cmp_lt_i32_e32 vcc, v181, v196
	s_waitcnt lgkmcnt(0)
	v_add_f32_e32 v184, v132, v133
	v_cndmask_b32_e32 v181, v221, v181, vcc
	v_lshlrev_b32_e32 v181, 2, v181
	ds_bpermute_b32 v185, v181, v184
	v_cmp_lt_i32_e32 vcc, v182, v196
	v_lshl_add_u64 v[132:133], v[164:165], 0, s[2:3]
	v_lshl_add_u64 v[132:133], v[174:175], 2, v[132:133]
	v_cndmask_b32_e32 v182, v221, v182, vcc
	v_lshlrev_b32_e32 v182, 2, v182
	s_waitcnt lgkmcnt(0)
	v_add_f32_e32 v174, v184, v185
	ds_bpermute_b32 v175, v182, v174
	v_pk_add_f32 v[128:129], v[192:193], v[128:129]
	v_pk_add_f32 v[130:131], v[194:195], v[130:131]
	v_cvt_pk_bf16_f32 v184, v128, v129
	v_cvt_pk_bf16_f32 v185, v130, v131
	global_store_dwordx4 v[206:207], v[128:131], off offset:256
	global_store_dwordx2 v[204:205], v[184:185], off offset:128
	s_and_saveexec_b64 s[2:3], s[4:5]
	s_cbranch_execz .LBB0_118
	s_waitcnt lgkmcnt(0)
	v_add_f32_e32 v174, v174, v175
	global_atomic_add_f32 v[132:133], v174, off

; template <int MODE, int HALF>
; __device__ void gemm_phase(const P& p, int layer, char* smem) {
;     ...
;         for (int hc = 0; hc < 2; ++hc) {
; #pragma unroll
;           for (int j = 0; j < 4; ++j)
; #pragma unroll
;             for (int n4 = 0; n4 < 4; ++n4) pf[(lqe * 4 + j) * 68 + n4 * 16 + lre] = acc[mi][hc * 4 + n4][j];
;           asm volatile("" ::: "memory");
; #pragma unroll
;           for (int it = 0; it < 4; ++it) {
;             int idx = it * 64 + lane, r = idx >> 4, ch = idx & 15;
;             float4 a4 = *(const float4*)(pf + r * 68 + ch * 4);
;             size_t grow = row0 + wm * 64 + mi * 16 + r;
;             int col = nt * 128 + hc * 64 + ch * 4;
;             float* xo = p.out + grow * 1024 + col;
;             float4 xr = (MODE == 1 && layer == 0) ? *(const float4*)(xin_row(p, grow) + col) : *(const float4*)xo;
;             float4 xn = make_float4(xr.x + a4.x, xr.y + a4.y, xr.z + a4.z, xr.w + a4.w);
;             *(float4*)xo = xn;
;             if (WRITE_XB) {
;               uint2 b2; b2.x = pack2(xn.x, xn.y); b2.y = pack2(xn.z, xn.w);
;               *(uint2*)((bf16_t*)(p.ws + OFF_XB) + grow * 1024 + col) = b2;
;               sq[it] += xn.x * xn.x + xn.y * xn.y + xn.z * xn.z + xn.w * xn.w;
;             }
.LBB0_124:
	s_or_b64 exec, exec, s[2:3]
	v_or_b32_e32 v138, 16, v172
	ds_write2_b32 v183, v116, v112 offset1:16
	ds_write2_b32 v183, v108, v104 offset0:32 offset1:48
	ds_write2_b32 v183, v117, v113 offset0:68 offset1:84
	ds_write2_b32 v183, v109, v105 offset0:100 offset1:116
	ds_write2_b32 v183, v118, v114 offset0:136 offset1:152
	ds_write2_b32 v183, v110, v106 offset0:168 offset1:184
	ds_write2_b32 v183, v119, v115 offset0:204 offset1:220
	ds_write2_b32 v183, v111, v107 offset0:236 offset1:252
	v_or_b32_e32 v108, v138, v152
	v_mov_b32_e32 v109, v173
	v_lshlrev_b64 v[104:105], 12, v[108:109]
	v_lshl_add_u64 v[104:105], s[56:57], 0, v[104:105]
	v_lshl_add_u64 v[124:125], v[104:105], 0, v[150:151]
	s_waitcnt vmcnt(13)
	s_nop 1
	v_mov_b32_e32 v104, v0
	v_mov_b32_e32 v105, v1
	v_mov_b32_e32 v106, v2
	v_mov_b32_e32 v107, v3
	v_lshlrev_b64 v[116:117], 11, v[108:109]
	ds_read_b128 v[108:111], v180 offset:49152
	ds_read_b128 v[112:115], v180 offset:50240
	s_waitcnt lgkmcnt(10)
	v_mov_b32_e32 v121, v173
	v_or_b32_e32 v120, v138, v166
	v_lshlrev_b64 v[118:119], 12, v[120:121]
	v_lshl_add_u64 v[116:117], s[50:51], 0, v[116:117]
	v_lshl_add_u64 v[118:119], s[56:57], 0, v[118:119]
	v_lshl_add_u64 v[126:127], v[116:117], 0, v[148:149]
	v_lshl_add_u64 v[128:129], v[118:119], 0, v[150:151]
	v_mov_b32_e32 v123, v173
	v_or_b32_e32 v122, v138, v168
	v_lshlrev_b64 v[140:141], 11, v[122:123]
	v_mov_b32_e32 v139, v173
	v_or_b32_e32 v138, v138, v170
	v_lshlrev_b64 v[142:143], 12, v[138:139]
	v_lshl_add_u64 v[140:141], s[50:51], 0, v[140:141]
	v_lshl_add_u64 v[142:143], s[56:57], 0, v[142:143]
	v_lshl_add_u64 v[140:141], v[140:141], 0, v[148:149]
	v_lshl_add_u64 v[142:143], v[142:143], 0, v[150:151]
	v_lshlrev_b64 v[138:139], 11, v[138:139]
	v_lshl_add_u64 v[138:139], s[50:51], 0, v[138:139]
	v_lshl_add_u64 v[138:139], v[138:139], 0, v[148:149]
	s_waitcnt lgkmcnt(1)
	v_pk_add_f32 v[116:117], v[108:109], v[104:105]
	v_pk_add_f32 v[118:119], v[110:111], v[106:107]
	v_cvt_pk_bf16_f32 v104, v116, v117
	v_cvt_pk_bf16_f32 v105, v118, v119
	global_store_dwordx4 v[124:125], v[116:119], off
	global_store_dwordx2 v[126:127], v[104:105], off
	s_waitcnt vmcnt(14)
	s_nop 1
	v_mov_b32_e32 v104, v4
	v_mov_b32_e32 v105, v5
	v_mov_b32_e32 v106, v6
	v_mov_b32_e32 v107, v7
	v_lshlrev_b64 v[108:109], 11, v[120:121]
	v_lshlrev_b64 v[110:111], 12, v[122:123]
	v_lshl_add_u64 v[108:109], s[50:51], 0, v[108:109]
	v_lshl_add_u64 v[110:111], s[56:57], 0, v[110:111]
	v_lshl_add_u64 v[130:131], v[108:109], 0, v[148:149]
	v_lshl_add_u64 v[136:137], v[110:111], 0, v[150:151]
	v_pk_mul_f32 v[116:117], v[116:117], v[116:117]
	v_pk_mul_f32 v[118:119], v[118:119], v[118:119]
	v_add_f32_e32 v116, v116, v117
	v_add_f32_e32 v116, v116, v118
	v_add_f32_e32 v116, v116, v119
	s_waitcnt lgkmcnt(0)
	v_pk_add_f32 v[104:105], v[112:113], v[104:105]
	v_pk_add_f32 v[106:107], v[114:115], v[106:107]
	v_cvt_pk_bf16_f32 v108, v104, v105
	v_cvt_pk_bf16_f32 v109, v106, v107
	global_store_dwordx4 v[128:129], v[104:107], off
	global_store_dwordx2 v[130:131], v[108:109], off
	s_waitcnt vmcnt(15)
	s_nop 1
	v_mov_b32_e32 v108, v8
	v_mov_b32_e32 v109, v9
	v_mov_b32_e32 v110, v10
	v_mov_b32_e32 v111, v11
	ds_read_b128 v[112:115], v180 offset:51328
	ds_read_b128 v[120:123], v180 offset:52416
	s_waitcnt lgkmcnt(1)
	v_pk_add_f32 v[112:113], v[112:113], v[108:109]
	v_pk_add_f32 v[114:115], v[114:115], v[110:111]
	v_cvt_pk_bf16_f32 v108, v112, v113
	v_cvt_pk_bf16_f32 v109, v114, v115
	global_store_dwordx4 v[136:137], v[112:115], off
	global_store_dwordx2 v[140:141], v[108:109], off
	s_waitcnt vmcnt(16)
	s_nop 1
	v_mov_b32_e32 v108, v12
	v_mov_b32_e32 v109, v13
	v_mov_b32_e32 v110, v14
	v_mov_b32_e32 v111, v15
	s_waitcnt lgkmcnt(0)
	v_pk_add_f32 v[108:109], v[120:121], v[108:109]
	v_pk_add_f32 v[110:111], v[122:123], v[110:111]
	v_cvt_pk_bf16_f32 v120, v108, v109
	v_cvt_pk_bf16_f32 v121, v110, v111
	global_store_dwordx4 v[142:143], v[108:111], off
	global_store_dwordx2 v[138:139], v[120:121], off
	ds_write2_b32 v183, v100, v96 offset1:16
	ds_write2_b32 v183, v92, v88 offset0:32 offset1:48
	ds_write2_b32 v183, v101, v97 offset0:68 offset1:84
	ds_write2_b32 v183, v93, v89 offset0:100 offset1:116
	ds_write2_b32 v183, v102, v98 offset0:136 offset1:152
	ds_write2_b32 v183, v94, v90 offset0:168 offset1:184
	ds_write2_b32 v183, v103, v99 offset0:204 offset1:220
	ds_write2_b32 v183, v95, v91 offset0:236 offset1:252
	s_waitcnt vmcnt(17)
; template <int MODE, int HALF>
; __device__ void gemm_phase(const P& p, int layer, char* smem) {
;     ...
;         for (int hc = 0; hc < 2; ++hc) {
; #pragma unroll
;           for (int j = 0; j < 4; ++j)
; #pragma unroll
;             for (int n4 = 0; n4 < 4; ++n4) pf[(lqe * 4 + j) * 68 + n4 * 16 + lre] = acc[mi][hc * 4 + n4][j];
;           asm volatile("" ::: "memory");
; #pragma unroll
;           for (int it = 0; it < 4; ++it) {
;             int idx = it * 64 + lane, r = idx >> 4, ch = idx & 15;
;             float4 a4 = *(const float4*)(pf + r * 68 + ch * 4);
;             size_t grow = row0 + wm * 64 + mi * 16 + r;
;             int col = nt * 128 + hc * 64 + ch * 4;
;             float* xo = p.out + grow * 1024 + col;
;             float4 xr = (MODE == 1 && layer == 0) ? *(const float4*)(xin_row(p, grow) + col) : *(const float4*)xo;
;             float4 xn = make_float4(xr.x + a4.x, xr.y + a4.y, xr.z + a4.z, xr.w + a4.w);
;             *(float4*)xo = xn;
;             if (WRITE_XB) {
;               uint2 b2; b2.x = pack2(xn.x, xn.y); b2.y = pack2(xn.z, xn.w);
;               *(uint2*)((bf16_t*)(p.ws + OFF_XB) + grow * 1024 + col) = b2;
;               sq[it] += xn.x * xn.x + xn.y * xn.y + xn.z * xn.z + xn.w * xn.w;
;             }
;           }
;           asm volatile("" ::: "memory");
;         }
;         if (WRITE_XB) {
; #pragma unroll
;           for (int it = 0; it < 4; ++it) {
;             float s = sq[it];
;             s += __shfl_xor(s, 1); s += __shfl_xor(s, 2); s += __shfl_xor(s, 4); s += __shfl_xor(s, 8);
;             if ((lane & 15) == 0) atomicAdd(((MODE == 1) ? RSa : RSb) + row0 + wm * 64 + mi * 16 + it * 4 + lqe, s);
;           }
	s_nop 1
	v_mov_b32_e32 v88, v16
	v_mov_b32_e32 v89, v17
	v_mov_b32_e32 v90, v18
	v_mov_b32_e32 v91, v19
	ds_read_b128 v[92:95], v180 offset:49152
	ds_read_b128 v[96:99], v180 offset:50240
	s_waitcnt lgkmcnt(1)
	v_pk_add_f32 v[100:101], v[92:93], v[88:89]
	v_pk_add_f32 v[102:103], v[94:95], v[90:91]
	v_cvt_pk_bf16_f32 v88, v100, v101
	v_cvt_pk_bf16_f32 v89, v102, v103
	global_store_dwordx4 v[124:125], v[100:103], off offset:256
	global_store_dwordx2 v[126:127], v[88:89], off offset:128
	s_waitcnt vmcnt(18)
	s_nop 1
	v_mov_b32_e32 v88, v20
	v_mov_b32_e32 v89, v21
	v_mov_b32_e32 v90, v22
	v_mov_b32_e32 v91, v23
	v_pk_mul_f32 v[100:101], v[100:101], v[100:101]
	v_pk_mul_f32 v[102:103], v[102:103], v[102:103]
	v_add_f32_e32 v100, v100, v101
	v_add_f32_e32 v100, v100, v102
	v_add_f32_e32 v100, v100, v103
	v_add_f32_e32 v100, v116, v100
	ds_bpermute_b32 v101, v134, v100
	s_waitcnt lgkmcnt(0)
	v_add_f32_e32 v100, v100, v101
	ds_bpermute_b32 v101, v135, v100
	s_waitcnt lgkmcnt(0)
	v_add_f32_e32 v100, v100, v101
	ds_bpermute_b32 v101, v181, v100
	s_waitcnt lgkmcnt(0)
	v_add_f32_e32 v100, v100, v101
	ds_bpermute_b32 v101, v182, v100
	v_pk_add_f32 v[88:89], v[96:97], v[88:89]
	v_pk_add_f32 v[90:91], v[98:99], v[90:91]
	v_cvt_pk_bf16_f32 v92, v88, v89
	v_cvt_pk_bf16_f32 v93, v90, v91
	global_store_dwordx4 v[128:129], v[88:91], off offset:256
	global_store_dwordx2 v[130:131], v[92:93], off offset:128
	s_waitcnt vmcnt(19)
	s_nop 1
	v_mov_b32_e32 v92, v208
	v_mov_b32_e32 v93, v209
	v_mov_b32_e32 v94, v210
	v_mov_b32_e32 v95, v211
	ds_read_b128 v[96:99], v180 offset:51328
	ds_read_b128 v[120:123], v180 offset:52416
	s_waitcnt lgkmcnt(1)
	v_pk_add_f32 v[92:93], v[96:97], v[92:93]
	v_pk_add_f32 v[94:95], v[98:99], v[94:95]
	v_cvt_pk_bf16_f32 v96, v92, v93
	v_cvt_pk_bf16_f32 v97, v94, v95
	global_store_dwordx4 v[136:137], v[92:95], off offset:256
	global_store_dwordx2 v[140:141], v[96:97], off offset:128
	s_waitcnt vmcnt(20)
	s_nop 1
	v_mov_b32_e32 v96, v212
	v_mov_b32_e32 v97, v213
	v_mov_b32_e32 v98, v214
	v_mov_b32_e32 v99, v215
	v_mov_b32_e32 v218, 0x20000
	v_mov_b32_e32 v219, 0
	v_lshl_add_u64 v[218:219], v[216:217], 0, v[218:219]
	global_load_dwordx4 v[0:3], v[218:219], off
	v_mov_b32_e32 v218, 0x24000
	v_mov_b32_e32 v219, 0
	v_lshl_add_u64 v[218:219], v[216:217], 0, v[218:219]
	global_load_dwordx4 v[4:7], v[218:219], off
	v_mov_b32_e32 v218, 0x28000
	v_mov_b32_e32 v219, 0
	v_lshl_add_u64 v[218:219], v[216:217], 0, v[218:219]
	global_load_dwordx4 v[8:11], v[218:219], off
	v_mov_b32_e32 v218, 0x2c000
	v_mov_b32_e32 v219, 0
	v_lshl_add_u64 v[218:219], v[216:217], 0, v[218:219]
	global_load_dwordx4 v[12:15], v[218:219], off
	v_mov_b32_e32 v218, 0x20000
	v_mov_b32_e32 v219, 0
	v_lshl_add_u64 v[218:219], v[216:217], 0, v[218:219]
	global_load_dwordx4 v[16:19], v[218:219], off offset:256
	v_mov_b32_e32 v218, 0x24000
	v_mov_b32_e32 v219, 0
	v_lshl_add_u64 v[218:219], v[216:217], 0, v[218:219]
	global_load_dwordx4 v[20:23], v[218:219], off offset:256
	v_mov_b32_e32 v218, 0x28000
	v_mov_b32_e32 v219, 0
	v_lshl_add_u64 v[218:219], v[216:217], 0, v[218:219]
	global_load_dwordx4 v[208:211], v[218:219], off offset:256
	v_mov_b32_e32 v218, 0x2c000
	v_mov_b32_e32 v219, 0
	v_lshl_add_u64 v[218:219], v[216:217], 0, v[218:219]
	global_load_dwordx4 v[212:215], v[218:219], off offset:256
	s_waitcnt lgkmcnt(0)
	v_pk_add_f32 v[96:97], v[120:121], v[96:97]
	v_pk_add_f32 v[98:99], v[122:123], v[98:99]
	v_cvt_pk_bf16_f32 v102, v96, v97
	v_cvt_pk_bf16_f32 v103, v98, v99
	global_store_dwordx4 v[142:143], v[96:99], off offset:256
	global_store_dwordx2 v[138:139], v[102:103], off offset:128
	s_and_saveexec_b64 s[2:3], s[4:5]
	s_cbranch_execz .LBB0_126
	v_add_f32_e32 v100, v100, v101
	global_atomic_add_f32 v[132:133], v100, off offset:64

; template <int MODE, int HALF>
; __device__ void gemm_phase(const P& p, int layer, char* smem) {
;     ...
;         for (int hc = 0; hc < 2; ++hc) {
; #pragma unroll
;           for (int j = 0; j < 4; ++j)
; #pragma unroll
;             for (int n4 = 0; n4 < 4; ++n4) pf[(lqe * 4 + j) * 68 + n4 * 16 + lre] = acc[mi][hc * 4 + n4][j];
;           asm volatile("" ::: "memory");
; #pragma unroll
;           for (int it = 0; it < 4; ++it) {
;             int idx = it * 64 + lane, r = idx >> 4, ch = idx & 15;
;             float4 a4 = *(const float4*)(pf + r * 68 + ch * 4);
;             size_t grow = row0 + wm * 64 + mi * 16 + r;
;             int col = nt * 128 + hc * 64 + ch * 4;
;             float* xo = p.out + grow * 1024 + col;
;             float4 xr = (MODE == 1 && layer == 0) ? *(const float4*)(xin_row(p, grow) + col) : *(const float4*)xo;
;             float4 xn = make_float4(xr.x + a4.x, xr.y + a4.y, xr.z + a4.z, xr.w + a4.w);
;             *(float4*)xo = xn;
;             if (WRITE_XB) {
;               uint2 b2; b2.x = pack2(xn.x, xn.y); b2.y = pack2(xn.z, xn.w);
;               *(uint2*)((bf16_t*)(p.ws + OFF_XB) + grow * 1024 + col) = b2;
;               sq[it] += xn.x * xn.x + xn.y * xn.y + xn.z * xn.z + xn.w * xn.w;
;             }
.LBB0_132:
	s_or_b64 exec, exec, s[2:3]
	v_or_b32_e32 v102, 32, v172
	ds_write2_b32 v183, v84, v80 offset1:16
	ds_write2_b32 v183, v76, v72 offset0:32 offset1:48
	ds_write2_b32 v183, v85, v81 offset0:68 offset1:84
	ds_write2_b32 v183, v77, v73 offset0:100 offset1:116
	ds_write2_b32 v183, v86, v82 offset0:136 offset1:152
	ds_write2_b32 v183, v78, v74 offset0:168 offset1:184
	ds_write2_b32 v183, v87, v83 offset0:204 offset1:220
	ds_write2_b32 v183, v79, v75 offset0:236 offset1:252
	v_or_b32_e32 v76, v102, v152
	v_mov_b32_e32 v77, v173
	v_lshlrev_b64 v[72:73], 12, v[76:77]
	v_lshl_add_u64 v[72:73], s[56:57], 0, v[72:73]
	v_lshl_add_u64 v[92:93], v[72:73], 0, v[150:151]
	s_waitcnt vmcnt(13)
	s_nop 1
	v_mov_b32_e32 v72, v0
	v_mov_b32_e32 v73, v1
	v_mov_b32_e32 v74, v2
	v_mov_b32_e32 v75, v3
	v_lshlrev_b64 v[84:85], 11, v[76:77]
	ds_read_b128 v[76:79], v180 offset:49152
	ds_read_b128 v[80:83], v180 offset:50240
	s_waitcnt lgkmcnt(10)
	v_mov_b32_e32 v89, v173
	v_or_b32_e32 v88, v102, v166
	v_lshlrev_b64 v[86:87], 12, v[88:89]
	v_lshl_add_u64 v[84:85], s[50:51], 0, v[84:85]
	v_lshl_add_u64 v[86:87], s[56:57], 0, v[86:87]
	v_lshl_add_u64 v[94:95], v[84:85], 0, v[148:149]
	v_lshl_add_u64 v[96:97], v[86:87], 0, v[150:151]
	v_mov_b32_e32 v91, v173
	v_or_b32_e32 v90, v102, v168
	v_lshlrev_b64 v[104:105], 11, v[90:91]
	v_mov_b32_e32 v103, v173
	v_or_b32_e32 v102, v102, v170
	v_lshlrev_b64 v[106:107], 12, v[102:103]
	v_lshl_add_u64 v[104:105], s[50:51], 0, v[104:105]
	v_lshl_add_u64 v[106:107], s[56:57], 0, v[106:107]
	v_lshl_add_u64 v[104:105], v[104:105], 0, v[148:149]
	v_lshl_add_u64 v[106:107], v[106:107], 0, v[150:151]
	v_lshlrev_b64 v[102:103], 11, v[102:103]
	v_lshl_add_u64 v[102:103], s[50:51], 0, v[102:103]
	v_lshl_add_u64 v[102:103], v[102:103], 0, v[148:149]
	s_waitcnt lgkmcnt(1)
	v_pk_add_f32 v[84:85], v[76:77], v[72:73]
	v_pk_add_f32 v[86:87], v[78:79], v[74:75]
	v_cvt_pk_bf16_f32 v72, v84, v85
	v_cvt_pk_bf16_f32 v73, v86, v87
	global_store_dwordx4 v[92:93], v[84:87], off
	global_store_dwordx2 v[94:95], v[72:73], off
	s_waitcnt vmcnt(14)
	s_nop 1
	v_mov_b32_e32 v72, v4
	v_mov_b32_e32 v73, v5
	v_mov_b32_e32 v74, v6
	v_mov_b32_e32 v75, v7
	v_lshlrev_b64 v[76:77], 11, v[88:89]
	v_lshlrev_b64 v[78:79], 12, v[90:91]
	v_lshl_add_u64 v[76:77], s[50:51], 0, v[76:77]
	v_lshl_add_u64 v[78:79], s[56:57], 0, v[78:79]
	v_lshl_add_u64 v[98:99], v[76:77], 0, v[148:149]
	v_lshl_add_u64 v[100:101], v[78:79], 0, v[150:151]
	v_pk_mul_f32 v[84:85], v[84:85], v[84:85]
	v_pk_mul_f32 v[86:87], v[86:87], v[86:87]
	v_add_f32_e32 v84, v84, v85
	v_add_f32_e32 v84, v84, v86
	v_add_f32_e32 v84, v84, v87
	s_waitcnt lgkmcnt(0)
	v_pk_add_f32 v[72:73], v[80:81], v[72:73]
	v_pk_add_f32 v[74:75], v[82:83], v[74:75]
	v_cvt_pk_bf16_f32 v76, v72, v73
	v_cvt_pk_bf16_f32 v77, v74, v75
	global_store_dwordx4 v[96:97], v[72:75], off
	global_store_dwordx2 v[98:99], v[76:77], off
	s_waitcnt vmcnt(15)
	s_nop 1
	v_mov_b32_e32 v76, v8
	v_mov_b32_e32 v77, v9
	v_mov_b32_e32 v78, v10
	v_mov_b32_e32 v79, v11
	ds_read_b128 v[80:83], v180 offset:51328
	ds_read_b128 v[88:91], v180 offset:52416
	s_waitcnt lgkmcnt(1)
	v_pk_add_f32 v[80:81], v[80:81], v[76:77]
	v_pk_add_f32 v[82:83], v[82:83], v[78:79]
	v_cvt_pk_bf16_f32 v76, v80, v81
	v_cvt_pk_bf16_f32 v77, v82, v83
	global_store_dwordx4 v[100:101], v[80:83], off
	global_store_dwordx2 v[104:105], v[76:77], off
	s_waitcnt vmcnt(16)
	s_nop 1
	v_mov_b32_e32 v76, v12
	v_mov_b32_e32 v77, v13
	v_mov_b32_e32 v78, v14
	v_mov_b32_e32 v79, v15
	s_waitcnt lgkmcnt(0)
	v_pk_add_f32 v[76:77], v[88:89], v[76:77]
	v_pk_add_f32 v[78:79], v[90:91], v[78:79]
	v_cvt_pk_bf16_f32 v88, v76, v77
	v_cvt_pk_bf16_f32 v89, v78, v79
	global_store_dwordx4 v[106:107], v[76:79], off
	global_store_dwordx2 v[102:103], v[88:89], off
	ds_write2_b32 v183, v68, v64 offset1:16
	ds_write2_b32 v183, v60, v56 offset0:32 offset1:48
	ds_write2_b32 v183, v69, v65 offset0:68 offset1:84
	ds_write2_b32 v183, v61, v57 offset0:100 offset1:116
	ds_write2_b32 v183, v70, v66 offset0:136 offset1:152
	ds_write2_b32 v183, v62, v58 offset0:168 offset1:184
	ds_write2_b32 v183, v71, v67 offset0:204 offset1:220
	ds_write2_b32 v183, v63, v59 offset0:236 offset1:252
	s_waitcnt vmcnt(17)
; template <int MODE, int HALF>
; __device__ void gemm_phase(const P& p, int layer, char* smem) {
;     ...
;         for (int hc = 0; hc < 2; ++hc) {
; #pragma unroll
;           for (int j = 0; j < 4; ++j)
; #pragma unroll
;             for (int n4 = 0; n4 < 4; ++n4) pf[(lqe * 4 + j) * 68 + n4 * 16 + lre] = acc[mi][hc * 4 + n4][j];
;           asm volatile("" ::: "memory");
; #pragma unroll
;           for (int it = 0; it < 4; ++it) {
;             int idx = it * 64 + lane, r = idx >> 4, ch = idx & 15;
;             float4 a4 = *(const float4*)(pf + r * 68 + ch * 4);
;             size_t grow = row0 + wm * 64 + mi * 16 + r;
;             int col = nt * 128 + hc * 64 + ch * 4;
;             float* xo = p.out + grow * 1024 + col;
;             float4 xr = (MODE == 1 && layer == 0) ? *(const float4*)(xin_row(p, grow) + col) : *(const float4*)xo;
;             float4 xn = make_float4(xr.x + a4.x, xr.y + a4.y, xr.z + a4.z, xr.w + a4.w);
;             *(float4*)xo = xn;
;             if (WRITE_XB) {
;               uint2 b2; b2.x = pack2(xn.x, xn.y); b2.y = pack2(xn.z, xn.w);
;               *(uint2*)((bf16_t*)(p.ws + OFF_XB) + grow * 1024 + col) = b2;
;               sq[it] += xn.x * xn.x + xn.y * xn.y + xn.z * xn.z + xn.w * xn.w;
;             }
;           }
;           asm volatile("" ::: "memory");
;         }
;         if (WRITE_XB) {
; #pragma unroll
;           for (int it = 0; it < 4; ++it) {
;             float s = sq[it];
;             s += __shfl_xor(s, 1); s += __shfl_xor(s, 2); s += __shfl_xor(s, 4); s += __shfl_xor(s, 8);
;             if ((lane & 15) == 0) atomicAdd(((MODE == 1) ? RSa : RSb) + row0 + wm * 64 + mi * 16 + it * 4 + lqe, s);
;           }
	s_nop 1
	v_mov_b32_e32 v56, v16
	v_mov_b32_e32 v57, v17
	v_mov_b32_e32 v58, v18
	v_mov_b32_e32 v59, v19
	ds_read_b128 v[60:63], v180 offset:49152
	ds_read_b128 v[64:67], v180 offset:50240
	s_waitcnt lgkmcnt(1)
	v_pk_add_f32 v[68:69], v[60:61], v[56:57]
	v_pk_add_f32 v[70:71], v[62:63], v[58:59]
	v_cvt_pk_bf16_f32 v56, v68, v69
	v_cvt_pk_bf16_f32 v57, v70, v71
	global_store_dwordx4 v[92:93], v[68:71], off offset:256
	global_store_dwordx2 v[94:95], v[56:57], off offset:128
	s_waitcnt vmcnt(18)
	s_nop 1
	v_mov_b32_e32 v56, v20
	v_mov_b32_e32 v57, v21
	v_mov_b32_e32 v58, v22
	v_mov_b32_e32 v59, v23
	v_pk_mul_f32 v[68:69], v[68:69], v[68:69]
	v_pk_mul_f32 v[70:71], v[70:71], v[70:71]
	v_add_f32_e32 v68, v68, v69
	v_add_f32_e32 v68, v68, v70
	v_add_f32_e32 v68, v68, v71
	v_add_f32_e32 v68, v84, v68
	ds_bpermute_b32 v69, v134, v68
	s_waitcnt lgkmcnt(0)
	v_add_f32_e32 v68, v68, v69
	ds_bpermute_b32 v69, v135, v68
	s_waitcnt lgkmcnt(0)
	v_add_f32_e32 v68, v68, v69
	ds_bpermute_b32 v69, v181, v68
	s_waitcnt lgkmcnt(0)
	v_add_f32_e32 v68, v68, v69
	ds_bpermute_b32 v69, v182, v68
	v_pk_add_f32 v[56:57], v[64:65], v[56:57]
	v_pk_add_f32 v[58:59], v[66:67], v[58:59]
	v_cvt_pk_bf16_f32 v60, v56, v57
	v_cvt_pk_bf16_f32 v61, v58, v59
	global_store_dwordx4 v[96:97], v[56:59], off offset:256
	global_store_dwordx2 v[98:99], v[60:61], off offset:128
	s_waitcnt vmcnt(19)
	s_nop 1
	v_mov_b32_e32 v60, v208
	v_mov_b32_e32 v61, v209
	v_mov_b32_e32 v62, v210
	v_mov_b32_e32 v63, v211
	ds_read_b128 v[64:67], v180 offset:51328
	ds_read_b128 v[88:91], v180 offset:52416
	s_waitcnt lgkmcnt(1)
	v_pk_add_f32 v[60:61], v[64:65], v[60:61]
	v_pk_add_f32 v[62:63], v[66:67], v[62:63]
	v_cvt_pk_bf16_f32 v64, v60, v61
	v_cvt_pk_bf16_f32 v65, v62, v63
	global_store_dwordx4 v[100:101], v[60:63], off offset:256
	global_store_dwordx2 v[104:105], v[64:65], off offset:128
	s_waitcnt vmcnt(20)
	s_nop 1
	v_mov_b32_e32 v64, v212
	v_mov_b32_e32 v65, v213
	v_mov_b32_e32 v66, v214
	v_mov_b32_e32 v67, v215
	v_mov_b32_e32 v218, 0x30000
	v_mov_b32_e32 v219, 0
	v_lshl_add_u64 v[218:219], v[216:217], 0, v[218:219]
	global_load_dwordx4 v[0:3], v[218:219], off
	v_mov_b32_e32 v218, 0x34000
	v_mov_b32_e32 v219, 0
	v_lshl_add_u64 v[218:219], v[216:217], 0, v[218:219]
	global_load_dwordx4 v[4:7], v[218:219], off
	v_mov_b32_e32 v218, 0x38000
	v_mov_b32_e32 v219, 0
	v_lshl_add_u64 v[218:219], v[216:217], 0, v[218:219]
	global_load_dwordx4 v[8:11], v[218:219], off
	v_mov_b32_e32 v218, 0x3c000
	v_mov_b32_e32 v219, 0
	v_lshl_add_u64 v[218:219], v[216:217], 0, v[218:219]
	global_load_dwordx4 v[12:15], v[218:219], off
	v_mov_b32_e32 v218, 0x30000
	v_mov_b32_e32 v219, 0
	v_lshl_add_u64 v[218:219], v[216:217], 0, v[218:219]
	global_load_dwordx4 v[16:19], v[218:219], off offset:256
	v_mov_b32_e32 v218, 0x34000
	v_mov_b32_e32 v219, 0
	v_lshl_add_u64 v[218:219], v[216:217], 0, v[218:219]
	global_load_dwordx4 v[20:23], v[218:219], off offset:256
	v_mov_b32_e32 v218, 0x38000
	v_mov_b32_e32 v219, 0
	v_lshl_add_u64 v[218:219], v[216:217], 0, v[218:219]
	global_load_dwordx4 v[208:211], v[218:219], off offset:256
	v_mov_b32_e32 v218, 0x3c000
	v_mov_b32_e32 v219, 0
	v_lshl_add_u64 v[218:219], v[216:217], 0, v[218:219]
	global_load_dwordx4 v[212:215], v[218:219], off offset:256
	s_waitcnt lgkmcnt(0)
	v_pk_add_f32 v[64:65], v[88:89], v[64:65]
	v_pk_add_f32 v[66:67], v[90:91], v[66:67]
	v_cvt_pk_bf16_f32 v70, v64, v65
	v_cvt_pk_bf16_f32 v71, v66, v67
	global_store_dwordx4 v[106:107], v[64:67], off offset:256
	global_store_dwordx2 v[102:103], v[70:71], off offset:128
	s_and_saveexec_b64 s[2:3], s[4:5]
	s_cbranch_execz .LBB0_134
	v_add_f32_e32 v68, v68, v69
	global_atomic_add_f32 v[132:133], v68, off offset:128

; template <int MODE, int HALF>
; __device__ void gemm_phase(const P& p, int layer, char* smem) {
;     ...
;         for (int hc = 0; hc < 2; ++hc) {
; #pragma unroll
;           for (int j = 0; j < 4; ++j)
; #pragma unroll
;             for (int n4 = 0; n4 < 4; ++n4) pf[(lqe * 4 + j) * 68 + n4 * 16 + lre] = acc[mi][hc * 4 + n4][j];
;           asm volatile("" ::: "memory");
; #pragma unroll
;           for (int it = 0; it < 4; ++it) {
;             int idx = it * 64 + lane, r = idx >> 4, ch = idx & 15;
;             float4 a4 = *(const float4*)(pf + r * 68 + ch * 4);
;             size_t grow = row0 + wm * 64 + mi * 16 + r;
;             int col = nt * 128 + hc * 64 + ch * 4;
;             float* xo = p.out + grow * 1024 + col;
;             float4 xr = (MODE == 1 && layer == 0) ? *(const float4*)(xin_row(p, grow) + col) : *(const float4*)xo;
;             float4 xn = make_float4(xr.x + a4.x, xr.y + a4.y, xr.z + a4.z, xr.w + a4.w);
;             *(float4*)xo = xn;
;             if (WRITE_XB) {
;               uint2 b2; b2.x = pack2(xn.x, xn.y); b2.y = pack2(xn.z, xn.w);
;               *(uint2*)((bf16_t*)(p.ws + OFF_XB) + grow * 1024 + col) = b2;
;               sq[it] += xn.x * xn.x + xn.y * xn.y + xn.z * xn.z + xn.w * xn.w;
;             }
;           }
;           asm volatile("" ::: "memory");
;         }
;         if (WRITE_XB) {
; #pragma unroll
;           for (int it = 0; it < 4; ++it) {
;             float s = sq[it];
;             s += __shfl_xor(s, 1); s += __shfl_xor(s, 2); s += __shfl_xor(s, 4); s += __shfl_xor(s, 8);
;             if ((lane & 15) == 0) atomicAdd(((MODE == 1) ? RSa : RSb) + row0 + wm * 64 + mi * 16 + it * 4 + lqe, s);
;           }
.LBB0_140:
	s_or_b64 exec, exec, s[2:3]
	v_or_b32_e32 v62, 48, v172
	v_or_b32_e32 v172, v62, v152
	ds_write2_b32 v183, v52, v48 offset1:16
	ds_write2_b32 v183, v44, v40 offset0:32 offset1:48
	ds_write2_b32 v183, v53, v49 offset0:68 offset1:84
	ds_write2_b32 v183, v45, v41 offset0:100 offset1:116
	ds_write2_b32 v183, v54, v50 offset0:136 offset1:152
	ds_write2_b32 v183, v46, v42 offset0:168 offset1:184
	ds_write2_b32 v183, v55, v51 offset0:204 offset1:220
	ds_write2_b32 v183, v47, v43 offset0:236 offset1:252
	v_lshlrev_b64 v[40:41], 12, v[172:173]
	v_lshl_add_u64 v[40:41], s[56:57], 0, v[40:41]
	v_lshl_add_u64 v[60:61], v[40:41], 0, v[150:151]
	s_waitcnt vmcnt(13)
	s_nop 1
	v_mov_b32_e32 v40, v0
	v_mov_b32_e32 v41, v1
	v_mov_b32_e32 v42, v2
	v_mov_b32_e32 v43, v3
	ds_read_b128 v[44:47], v180 offset:49152
	v_lshlrev_b64 v[48:49], 11, v[172:173]
	v_or_b32_e32 v172, v62, v166
	v_lshlrev_b64 v[50:51], 12, v[172:173]
	v_lshlrev_b64 v[52:53], 11, v[172:173]
	v_or_b32_e32 v172, v62, v168
	v_lshl_add_u64 v[48:49], s[50:51], 0, v[48:49]
	v_lshl_add_u64 v[52:53], s[50:51], 0, v[52:53]
	v_lshlrev_b64 v[54:55], 12, v[172:173]
	v_lshl_add_u64 v[64:65], v[48:49], 0, v[148:149]
	v_lshl_add_u64 v[48:49], s[56:57], 0, v[50:51]
	v_lshl_add_u64 v[68:69], v[52:53], 0, v[148:149]
	v_lshl_add_u64 v[52:53], s[56:57], 0, v[54:55]
	v_lshl_add_u64 v[58:59], v[48:49], 0, v[150:151]
	v_lshl_add_u64 v[66:67], v[52:53], 0, v[150:151]
	ds_read_b128 v[52:55], v180 offset:51328
	s_waitcnt lgkmcnt(10)
	v_lshlrev_b64 v[56:57], 11, v[172:173]
	v_or_b32_e32 v172, v62, v170
	v_lshl_add_u64 v[56:57], s[50:51], 0, v[56:57]
	v_lshlrev_b64 v[62:63], 12, v[172:173]
	v_lshl_add_u64 v[70:71], v[56:57], 0, v[148:149]
	v_lshl_add_u64 v[56:57], s[56:57], 0, v[62:63]
	v_lshl_add_u64 v[56:57], v[56:57], 0, v[150:151]
	v_lshlrev_b64 v[62:63], 11, v[172:173]
	v_lshl_add_u64 v[62:63], s[50:51], 0, v[62:63]
	v_lshl_add_u64 v[62:63], v[62:63], 0, v[148:149]
	ds_read_b128 v[72:75], v180 offset:52416
	s_waitcnt lgkmcnt(2)
	v_pk_add_f32 v[48:49], v[44:45], v[40:41]
	v_pk_add_f32 v[50:51], v[46:47], v[42:43]
	v_cvt_pk_bf16_f32 v40, v48, v49
	v_cvt_pk_bf16_f32 v41, v50, v51
	global_store_dwordx4 v[60:61], v[48:51], off
	global_store_dwordx2 v[64:65], v[40:41], off
	s_waitcnt vmcnt(14)
	s_nop 1
	v_mov_b32_e32 v40, v4
	v_mov_b32_e32 v41, v5
	v_mov_b32_e32 v42, v6
	v_mov_b32_e32 v43, v7
	ds_read_b128 v[44:47], v180 offset:50240
	s_waitcnt lgkmcnt(0)
	v_pk_add_f32 v[44:45], v[44:45], v[40:41]
	v_pk_add_f32 v[46:47], v[46:47], v[42:43]
	v_cvt_pk_bf16_f32 v40, v44, v45
	v_cvt_pk_bf16_f32 v41, v46, v47
	global_store_dwordx4 v[58:59], v[44:47], off
	global_store_dwordx2 v[68:69], v[40:41], off
	s_waitcnt vmcnt(15)
	s_nop 1
	v_mov_b32_e32 v40, v8
	v_mov_b32_e32 v41, v9
	v_mov_b32_e32 v42, v10
	v_mov_b32_e32 v43, v11
	v_pk_add_f32 v[40:41], v[52:53], v[40:41]
	v_pk_add_f32 v[42:43], v[54:55], v[42:43]
	v_cvt_pk_bf16_f32 v52, v40, v41
	v_cvt_pk_bf16_f32 v53, v42, v43
	global_store_dwordx4 v[66:67], v[40:43], off
	global_store_dwordx2 v[70:71], v[52:53], off
	s_waitcnt vmcnt(16)
	s_nop 1
	v_mov_b32_e32 v52, v12
	v_mov_b32_e32 v53, v13
	v_mov_b32_e32 v54, v14
	v_mov_b32_e32 v55, v15
	v_pk_add_f32 v[52:53], v[72:73], v[52:53]
	v_pk_add_f32 v[54:55], v[74:75], v[54:55]
	v_cvt_pk_bf16_f32 v72, v52, v53
	v_cvt_pk_bf16_f32 v73, v54, v55
	global_store_dwordx4 v[56:57], v[52:55], off
	global_store_dwordx2 v[62:63], v[72:73], off
	ds_write2_b32 v183, v24, v28 offset1:16
	ds_write2_b32 v183, v32, v36 offset0:32 offset1:48
	ds_write2_b32 v183, v25, v29 offset0:68 offset1:84
	ds_write2_b32 v183, v33, v37 offset0:100 offset1:116
	ds_write2_b32 v183, v26, v30 offset0:136 offset1:152
	ds_write2_b32 v183, v34, v38 offset0:168 offset1:184
	ds_write2_b32 v183, v27, v31 offset0:204 offset1:220
	ds_write2_b32 v183, v35, v39 offset0:236 offset1:252
	s_waitcnt vmcnt(17)
	s_nop 1
	v_mov_b32_e32 v24, v16
	v_mov_b32_e32 v25, v17
	v_mov_b32_e32 v26, v18
	v_mov_b32_e32 v27, v19
	ds_read_b128 v[28:31], v180 offset:49152
	ds_read_b128 v[36:39], v180 offset:51328
	s_waitcnt lgkmcnt(1)
	v_pk_add_f32 v[32:33], v[28:29], v[24:25]
	v_pk_add_f32 v[34:35], v[30:31], v[26:27]
	v_cvt_pk_bf16_f32 v24, v32, v33
	v_cvt_pk_bf16_f32 v25, v34, v35
	global_store_dwordx4 v[60:61], v[32:35], off offset:256
	global_store_dwordx2 v[64:65], v[24:25], off offset:128
	s_waitcnt vmcnt(18)
	s_nop 1
	v_mov_b32_e32 v24, v20
	v_mov_b32_e32 v25, v21
	v_mov_b32_e32 v26, v22
	v_mov_b32_e32 v27, v23
	ds_read_b128 v[28:31], v180 offset:50240
	v_pk_mul_f32 v[32:33], v[32:33], v[32:33]
	v_pk_mul_f32 v[34:35], v[34:35], v[34:35]
	v_add_f32_e32 v32, v32, v33
	v_add_f32_e32 v32, v32, v34
	v_add_f32_e32 v32, v32, v35
	s_waitcnt lgkmcnt(0)
	v_pk_add_f32 v[28:29], v[28:29], v[24:25]
	v_pk_add_f32 v[30:31], v[30:31], v[26:27]
	v_cvt_pk_bf16_f32 v24, v28, v29
	v_cvt_pk_bf16_f32 v25, v30, v31
	global_store_dwordx4 v[58:59], v[28:31], off offset:256
	global_store_dwordx2 v[68:69], v[24:25], off offset:128
	s_waitcnt vmcnt(19)
	s_nop 1
	v_mov_b32_e32 v24, v208
	v_mov_b32_e32 v25, v209
	v_mov_b32_e32 v26, v210
	v_mov_b32_e32 v27, v211
	v_pk_add_f32 v[24:25], v[36:37], v[24:25]
	v_pk_add_f32 v[26:27], v[38:39], v[26:27]
	v_cvt_pk_bf16_f32 v36, v24, v25
	v_cvt_pk_bf16_f32 v37, v26, v27
	global_store_dwordx4 v[66:67], v[24:27], off offset:256
	global_store_dwordx2 v[70:71], v[36:37], off offset:128
	s_waitcnt vmcnt(20)
	s_nop 1
	v_mov_b32_e32 v58, v212
	v_mov_b32_e32 v59, v213
	v_mov_b32_e32 v60, v214
	v_mov_b32_e32 v61, v215
	v_pk_mul_f32 v[36:37], v[48:49], v[48:49]
	v_pk_mul_f32 v[38:39], v[50:51], v[50:51]
	v_add_f32_e32 v36, v36, v37
	v_add_f32_e32 v36, v36, v38
	v_add_f32_e32 v36, v36, v39
	v_add_f32_e32 v32, v36, v32
	ds_bpermute_b32 v33, v134, v32
	s_waitcnt lgkmcnt(0)
	v_add_f32_e32 v32, v32, v33
	ds_bpermute_b32 v33, v135, v32
	s_waitcnt lgkmcnt(0)
	v_add_f32_e32 v36, v32, v33
	ds_bpermute_b32 v37, v181, v36
	ds_read_b128 v[32:35], v180 offset:52416
	s_waitcnt lgkmcnt(1)
	v_add_f32_e32 v36, v36, v37
	ds_bpermute_b32 v37, v182, v36
	s_waitcnt lgkmcnt(1)
	v_pk_add_f32 v[32:33], v[32:33], v[58:59]
	v_pk_add_f32 v[34:35], v[34:35], v[60:61]
	v_cvt_pk_bf16_f32 v38, v32, v33
	v_cvt_pk_bf16_f32 v39, v34, v35
	global_store_dwordx4 v[56:57], v[32:35], off offset:256
	global_store_dwordx2 v[62:63], v[38:39], off offset:128
	s_and_saveexec_b64 s[2:3], s[4:5]
	s_cbranch_execz .LBB0_142
	s_waitcnt lgkmcnt(0)
	v_add_f32_e32 v36, v36, v37
	global_atomic_add_f32 v[132:133], v36, off offset:192

; template <int MODE, int HALF>
; __device__ void gemm_phase(const P& p, int layer, char* smem) {
;     ...
;         for (int hc = 0; hc < 2; ++hc) {
; #pragma unroll
;           for (int j = 0; j < 4; ++j)
; #pragma unroll
;             for (int n4 = 0; n4 < 4; ++n4) pf[(lqe * 4 + j) * 68 + n4 * 16 + lre] = acc[mi][hc * 4 + n4][j];
;           asm volatile("" ::: "memory");
; #pragma unroll
;           for (int it = 0; it < 4; ++it) {
;             int idx = it * 64 + lane, r = idx >> 4, ch = idx & 15;
;             float4 a4 = *(const float4*)(pf + r * 68 + ch * 4);
;             size_t grow = row0 + wm * 64 + mi * 16 + r;
;             int col = nt * 128 + hc * 64 + ch * 4;
;             float* xo = p.out + grow * 1024 + col;
;             float4 xr = (MODE == 1 && layer == 0) ? *(const float4*)(xin_row(p, grow) + col) : *(const float4*)xo;
;             float4 xn = make_float4(xr.x + a4.x, xr.y + a4.y, xr.z + a4.z, xr.w + a4.w);
;             *(float4*)xo = xn;
.LBB0_173:
	s_ashr_i32 s5, s11, 31
	s_lshr_b32 s5, s5, 30
	s_add_i32 s5, s11, s5
	s_ashr_i32 s12, s5, 2
	s_and_b32 s5, s5, 0xfffffc
	s_sub_i32 s5, s11, s5
	v_mov_b32_e32 v175, v156
	v_mov_b32_e32 v170, v157
	v_lshl_or_b32 v180, s5, 8, v163
	s_movk_i32 s5, 0x440
	s_ashr_i32 s13, s12, 31
	v_lshlrev_b32_e32 v176, 2, v170
	v_mul_lo_u32 v175, v175, s5
	s_lshl_b64 s[12:13], s[12:13], 7
	v_add3_u32 v175, v161, v176, v175
	v_lshl_add_u64 v[170:171], s[12:13], 0, v[158:159]
	v_add_u32_e32 v175, 0xc000, v175
	ds_write2_b32 v175, v148, v144 offset1:16
	ds_write2_b32 v175, v140, v136 offset0:32 offset1:48
	ds_write2_b32 v175, v149, v145 offset0:68 offset1:84
	ds_write2_b32 v175, v141, v137 offset0:100 offset1:116
	ds_write2_b32 v175, v150, v146 offset0:136 offset1:152
	ds_write2_b32 v175, v142, v138 offset0:168 offset1:184
	ds_write2_b32 v175, v151, v147 offset0:204 offset1:220
	ds_write2_b32 v175, v143, v139 offset0:236 offset1:252
	v_or_b32_e32 v136, v170, v156
	v_mov_b32_e32 v137, v171
	v_ashrrev_i32_e32 v181, 31, v180
	v_lshlrev_b64 v[136:137], 12, v[136:137]
	v_lshl_add_u64 v[138:139], s[56:57], 0, v[136:137]
	v_lshlrev_b64 v[136:137], 2, v[180:181]
	v_lshl_add_u64 v[146:147], v[138:139], 0, v[136:137]
	v_mov_b32_e32 v192, v146
	v_mov_b32_e32 v193, v147
	v_mov_b32_e32 v194, 0
	v_mov_b32_e32 v195, 0
	v_lshl_add_u64 v[194:195], v[192:193], 0, v[194:195]
	global_load_dwordx4 v[0:3], v[194:195], off
	v_mov_b32_e32 v194, 0x4000
	v_mov_b32_e32 v195, 0
	v_lshl_add_u64 v[194:195], v[192:193], 0, v[194:195]
	global_load_dwordx4 v[4:7], v[194:195], off
	v_mov_b32_e32 v194, 0x8000
	v_mov_b32_e32 v195, 0
	v_lshl_add_u64 v[194:195], v[192:193], 0, v[194:195]
	global_load_dwordx4 v[8:11], v[194:195], off
	v_mov_b32_e32 v194, 0xc000
	v_mov_b32_e32 v195, 0
	v_lshl_add_u64 v[194:195], v[192:193], 0, v[194:195]
	global_load_dwordx4 v[12:15], v[194:195], off
	v_mov_b32_e32 v194, 0
	v_mov_b32_e32 v195, 0
	v_lshl_add_u64 v[194:195], v[192:193], 0, v[194:195]
	global_load_dwordx4 v[16:19], v[194:195], off offset:256
	v_mov_b32_e32 v194, 0x4000
	v_mov_b32_e32 v195, 0
	v_lshl_add_u64 v[194:195], v[192:193], 0, v[194:195]
	global_load_dwordx4 v[20:23], v[194:195], off offset:256
	v_mov_b32_e32 v194, 0x8000
	v_mov_b32_e32 v195, 0
	v_lshl_add_u64 v[194:195], v[192:193], 0, v[194:195]
	global_load_dwordx4 v[184:187], v[194:195], off offset:256
	v_mov_b32_e32 v194, 0xc000
	v_mov_b32_e32 v195, 0
	v_lshl_add_u64 v[194:195], v[192:193], 0, v[194:195]
	global_load_dwordx4 v[188:191], v[194:195], off offset:256
	s_waitcnt vmcnt(7)
	s_nop 1
	v_mov_b32_e32 v142, v0
	v_mov_b32_e32 v143, v1
	v_mov_b32_e32 v144, v2
	v_mov_b32_e32 v145, v3
	ds_read_b128 v[138:141], v172 offset:49152
	s_add_i32 s11, s11, s60
	s_cmpk_gt_i32 s11, 0x5ff
	s_waitcnt lgkmcnt(0)
	v_pk_add_f32 v[138:139], v[138:139], v[142:143]
	v_pk_add_f32 v[140:141], v[140:141], v[144:145]
	global_store_dwordx4 v[146:147], v[138:141], off
	s_nop 1
	v_or_b32_e32 v138, v170, v160
	v_mov_b32_e32 v139, v171
	v_lshlrev_b64 v[138:139], 12, v[138:139]
	v_lshl_add_u64 v[138:139], s[56:57], 0, v[138:139]
	v_lshl_add_u64 v[148:149], v[138:139], 0, v[136:137]
	s_waitcnt vmcnt(7)
	s_nop 1
	v_mov_b32_e32 v142, v4
	v_mov_b32_e32 v143, v5
	v_mov_b32_e32 v144, v6
	v_mov_b32_e32 v145, v7
	ds_read_b128 v[138:141], v172 offset:50240
	s_waitcnt lgkmcnt(0)
	v_pk_add_f32 v[138:139], v[138:139], v[142:143]
	v_pk_add_f32 v[140:141], v[140:141], v[144:145]
	global_store_dwordx4 v[148:149], v[138:141], off
	s_nop 1
	v_or_b32_e32 v138, v170, v162
	v_mov_b32_e32 v139, v171
	v_lshlrev_b64 v[138:139], 12, v[138:139]
	v_lshl_add_u64 v[138:139], s[56:57], 0, v[138:139]
	v_lshl_add_u64 v[150:151], v[138:139], 0, v[136:137]
	s_waitcnt vmcnt(7)
	s_nop 1
	v_mov_b32_e32 v142, v8
	v_mov_b32_e32 v143, v9
	v_mov_b32_e32 v144, v10
	v_mov_b32_e32 v145, v11
	ds_read_b128 v[138:141], v172 offset:51328
	s_waitcnt lgkmcnt(0)
	v_pk_add_f32 v[138:139], v[138:139], v[142:143]
	v_pk_add_f32 v[140:141], v[140:141], v[144:145]
	global_store_dwordx4 v[150:151], v[138:141], off
	s_nop 1
	v_or_b32_e32 v138, v170, v164
	v_mov_b32_e32 v139, v171
	v_lshlrev_b64 v[138:139], 12, v[138:139]
	v_lshl_add_u64 v[138:139], s[56:57], 0, v[138:139]
	v_lshl_add_u64 v[180:181], v[138:139], 0, v[136:137]
	s_waitcnt vmcnt(7)
	s_nop 1
	v_mov_b32_e32 v142, v12
	v_mov_b32_e32 v143, v13
	v_mov_b32_e32 v144, v14
	v_mov_b32_e32 v145, v15
	ds_read_b128 v[138:141], v172 offset:52416
	s_waitcnt lgkmcnt(0)
	v_pk_add_f32 v[138:139], v[138:139], v[142:143]
	v_pk_add_f32 v[140:141], v[140:141], v[144:145]
	global_store_dwordx4 v[180:181], v[138:141], off
	ds_write2_b32 v175, v132, v128 offset1:16
	ds_write2_b32 v175, v124, v120 offset0:32 offset1:48
	ds_write2_b32 v175, v133, v129 offset0:68 offset1:84
	ds_write2_b32 v175, v125, v121 offset0:100 offset1:116
	ds_write2_b32 v175, v134, v130 offset0:136 offset1:152
	ds_write2_b32 v175, v126, v122 offset0:168 offset1:184
	ds_write2_b32 v175, v135, v131 offset0:204 offset1:220
	ds_write2_b32 v175, v127, v123 offset0:236 offset1:252
	s_waitcnt vmcnt(7)
	s_nop 1
	v_mov_b32_e32 v124, v16
	v_mov_b32_e32 v125, v17
	v_mov_b32_e32 v126, v18
	v_mov_b32_e32 v127, v19
	ds_read_b128 v[120:123], v172 offset:49152
	s_waitcnt lgkmcnt(0)
	v_pk_add_f32 v[120:121], v[120:121], v[124:125]
	v_pk_add_f32 v[122:123], v[122:123], v[126:127]
	s_waitcnt vmcnt(6)
	s_nop 1
	v_mov_b32_e32 v124, v20
	v_mov_b32_e32 v125, v21
	v_mov_b32_e32 v126, v22
	v_mov_b32_e32 v127, v23
	s_nop 0
	global_store_dwordx4 v[146:147], v[120:123], off offset:256
	ds_read_b128 v[120:123], v172 offset:50240
	s_waitcnt lgkmcnt(0)
	v_pk_add_f32 v[120:121], v[120:121], v[124:125]
	v_pk_add_f32 v[122:123], v[122:123], v[126:127]
	s_waitcnt vmcnt(6)
; template <int MODE, int HALF>
; __device__ void gemm_phase(const P& p, int layer, char* smem) {
;     ...
;         for (int hc = 0; hc < 2; ++hc) {
; #pragma unroll
;           for (int j = 0; j < 4; ++j)
; #pragma unroll
;             for (int n4 = 0; n4 < 4; ++n4) pf[(lqe * 4 + j) * 68 + n4 * 16 + lre] = acc[mi][hc * 4 + n4][j];
;           asm volatile("" ::: "memory");
; #pragma unroll
;           for (int it = 0; it < 4; ++it) {
;             int idx = it * 64 + lane, r = idx >> 4, ch = idx & 15;
;             float4 a4 = *(const float4*)(pf + r * 68 + ch * 4);
;             size_t grow = row0 + wm * 64 + mi * 16 + r;
;             int col = nt * 128 + hc * 64 + ch * 4;
;             float* xo = p.out + grow * 1024 + col;
;             float4 xr = (MODE == 1 && layer == 0) ? *(const float4*)(xin_row(p, grow) + col) : *(const float4*)xo;
;             float4 xn = make_float4(xr.x + a4.x, xr.y + a4.y, xr.z + a4.z, xr.w + a4.w);
;             *(float4*)xo = xn;
	s_nop 1
	v_mov_b32_e32 v124, v184
	v_mov_b32_e32 v125, v185
	v_mov_b32_e32 v126, v186
	v_mov_b32_e32 v127, v187
	s_nop 0
	global_store_dwordx4 v[148:149], v[120:123], off offset:256
	ds_read_b128 v[120:123], v172 offset:51328
	s_waitcnt lgkmcnt(0)
	v_pk_add_f32 v[120:121], v[120:121], v[124:125]
	v_pk_add_f32 v[122:123], v[122:123], v[126:127]
	s_waitcnt vmcnt(6)
	s_nop 1
	v_mov_b32_e32 v124, v188
	v_mov_b32_e32 v125, v189
	v_mov_b32_e32 v126, v190
	v_mov_b32_e32 v127, v191
	v_mov_b32_e32 v194, 0x10000
	v_mov_b32_e32 v195, 0
	v_lshl_add_u64 v[194:195], v[192:193], 0, v[194:195]
	global_load_dwordx4 v[0:3], v[194:195], off
	v_mov_b32_e32 v194, 0x14000
	v_mov_b32_e32 v195, 0
	v_lshl_add_u64 v[194:195], v[192:193], 0, v[194:195]
	global_load_dwordx4 v[4:7], v[194:195], off
	v_mov_b32_e32 v194, 0x18000
	v_mov_b32_e32 v195, 0
	v_lshl_add_u64 v[194:195], v[192:193], 0, v[194:195]
	global_load_dwordx4 v[8:11], v[194:195], off
	v_mov_b32_e32 v194, 0x1c000
	v_mov_b32_e32 v195, 0
	v_lshl_add_u64 v[194:195], v[192:193], 0, v[194:195]
	global_load_dwordx4 v[12:15], v[194:195], off
	v_mov_b32_e32 v194, 0x10000
	v_mov_b32_e32 v195, 0
	v_lshl_add_u64 v[194:195], v[192:193], 0, v[194:195]
	global_load_dwordx4 v[16:19], v[194:195], off offset:256
	v_mov_b32_e32 v194, 0x14000
	v_mov_b32_e32 v195, 0
	v_lshl_add_u64 v[194:195], v[192:193], 0, v[194:195]
	global_load_dwordx4 v[20:23], v[194:195], off offset:256
	v_mov_b32_e32 v194, 0x18000
	v_mov_b32_e32 v195, 0
	v_lshl_add_u64 v[194:195], v[192:193], 0, v[194:195]
	global_load_dwordx4 v[184:187], v[194:195], off offset:256
	v_mov_b32_e32 v194, 0x1c000
	v_mov_b32_e32 v195, 0
	v_lshl_add_u64 v[194:195], v[192:193], 0, v[194:195]
	global_load_dwordx4 v[188:191], v[194:195], off offset:256
	s_nop 0
	global_store_dwordx4 v[150:151], v[120:123], off offset:256
	ds_read_b128 v[120:123], v172 offset:52416
	s_waitcnt lgkmcnt(0)
	v_pk_add_f32 v[120:121], v[120:121], v[124:125]
	v_pk_add_f32 v[122:123], v[122:123], v[126:127]
	global_store_dwordx4 v[180:181], v[120:123], off offset:256
	ds_write2_b32 v175, v116, v112 offset1:16
	ds_write2_b32 v175, v108, v104 offset0:32 offset1:48
	ds_write2_b32 v175, v117, v113 offset0:68 offset1:84
	ds_write2_b32 v175, v109, v105 offset0:100 offset1:116
	ds_write2_b32 v175, v118, v114 offset0:136 offset1:152
	ds_write2_b32 v175, v110, v106 offset0:168 offset1:184
	ds_write2_b32 v175, v119, v115 offset0:204 offset1:220
	ds_write2_b32 v175, v111, v107 offset0:236 offset1:252
	v_or_b32_e32 v120, 16, v170
	v_or_b32_e32 v104, v120, v156
	v_mov_b32_e32 v105, v171
	v_lshlrev_b64 v[104:105], 12, v[104:105]
	v_lshl_add_u64 v[104:105], s[56:57], 0, v[104:105]
	v_lshl_add_u64 v[104:105], v[104:105], 0, v[136:137]
	s_waitcnt vmcnt(9)
	s_nop 1
	v_mov_b32_e32 v110, v0
	v_mov_b32_e32 v111, v1
	v_mov_b32_e32 v112, v2
	v_mov_b32_e32 v113, v3
	ds_read_b128 v[106:109], v172 offset:49152
	s_waitcnt lgkmcnt(0)
	v_pk_add_f32 v[106:107], v[106:107], v[110:111]
	v_pk_add_f32 v[108:109], v[108:109], v[112:113]
	global_store_dwordx4 v[104:105], v[106:109], off
	ds_read_b128 v[108:111], v172 offset:50240
	s_nop 0
	v_or_b32_e32 v106, v120, v160
	v_mov_b32_e32 v107, v171
	v_lshlrev_b64 v[106:107], 12, v[106:107]
	v_lshl_add_u64 v[106:107], s[56:57], 0, v[106:107]
	v_lshl_add_u64 v[106:107], v[106:107], 0, v[136:137]
	s_waitcnt vmcnt(9)
	s_nop 1
	v_mov_b32_e32 v112, v4
	v_mov_b32_e32 v113, v5
	v_mov_b32_e32 v114, v6
	v_mov_b32_e32 v115, v7
	s_waitcnt lgkmcnt(0)
	v_pk_add_f32 v[108:109], v[108:109], v[112:113]
	v_pk_add_f32 v[110:111], v[110:111], v[114:115]
	global_store_dwordx4 v[106:107], v[108:111], off
	ds_read_b128 v[110:113], v172 offset:51328
	s_nop 0
	v_or_b32_e32 v108, v120, v162
	v_mov_b32_e32 v109, v171
	v_lshlrev_b64 v[108:109], 12, v[108:109]
	v_lshl_add_u64 v[108:109], s[56:57], 0, v[108:109]
	v_lshl_add_u64 v[108:109], v[108:109], 0, v[136:137]
	s_waitcnt vmcnt(9)
	s_nop 1
	v_mov_b32_e32 v114, v8
	v_mov_b32_e32 v115, v9
	v_mov_b32_e32 v116, v10
	v_mov_b32_e32 v117, v11
	s_waitcnt lgkmcnt(0)
	v_pk_add_f32 v[110:111], v[110:111], v[114:115]
	v_pk_add_f32 v[112:113], v[112:113], v[116:117]
	global_store_dwordx4 v[108:109], v[110:113], off
	s_nop 1
	v_or_b32_e32 v110, v120, v164
	v_mov_b32_e32 v111, v171
	v_lshlrev_b64 v[110:111], 12, v[110:111]
	v_lshl_add_u64 v[110:111], s[56:57], 0, v[110:111]
	v_lshl_add_u64 v[118:119], v[110:111], 0, v[136:137]
	s_waitcnt vmcnt(9)
	s_nop 1
	v_mov_b32_e32 v114, v12
	v_mov_b32_e32 v115, v13
	v_mov_b32_e32 v116, v14
	v_mov_b32_e32 v117, v15
	ds_read_b128 v[110:113], v172 offset:52416
	s_waitcnt lgkmcnt(0)
	v_pk_add_f32 v[110:111], v[110:111], v[114:115]
	v_pk_add_f32 v[112:113], v[112:113], v[116:117]
	global_store_dwordx4 v[118:119], v[110:113], off
	ds_write2_b32 v175, v100, v96 offset1:16
	ds_write2_b32 v175, v92, v88 offset0:32 offset1:48
	ds_write2_b32 v175, v101, v97 offset0:68 offset1:84
	ds_write2_b32 v175, v93, v89 offset0:100 offset1:116
	ds_write2_b32 v175, v102, v98 offset0:136 offset1:152
	ds_write2_b32 v175, v94, v90 offset0:168 offset1:184
	ds_write2_b32 v175, v103, v99 offset0:204 offset1:220
	ds_write2_b32 v175, v95, v91 offset0:236 offset1:252
	s_waitcnt vmcnt(9)
	s_nop 1
	v_mov_b32_e32 v92, v16
	v_mov_b32_e32 v93, v17
	v_mov_b32_e32 v94, v18
	v_mov_b32_e32 v95, v19
	ds_read_b128 v[88:91], v172 offset:49152
	s_waitcnt lgkmcnt(0)
	v_pk_add_f32 v[88:89], v[88:89], v[92:93]
	v_pk_add_f32 v[90:91], v[90:91], v[94:95]
	s_waitcnt vmcnt(8)
	s_nop 1
	v_mov_b32_e32 v92, v20
	v_mov_b32_e32 v93, v21
	v_mov_b32_e32 v94, v22
	v_mov_b32_e32 v95, v23
	s_nop 0
	global_store_dwordx4 v[104:105], v[88:91], off offset:256
	ds_read_b128 v[88:91], v172 offset:50240
	s_waitcnt lgkmcnt(0)
; template <int MODE, int HALF>
; __device__ void gemm_phase(const P& p, int layer, char* smem) {
;     ...
;         for (int hc = 0; hc < 2; ++hc) {
; #pragma unroll
;           for (int j = 0; j < 4; ++j)
; #pragma unroll
;             for (int n4 = 0; n4 < 4; ++n4) pf[(lqe * 4 + j) * 68 + n4 * 16 + lre] = acc[mi][hc * 4 + n4][j];
;           asm volatile("" ::: "memory");
; #pragma unroll
;           for (int it = 0; it < 4; ++it) {
;             int idx = it * 64 + lane, r = idx >> 4, ch = idx & 15;
;             float4 a4 = *(const float4*)(pf + r * 68 + ch * 4);
;             size_t grow = row0 + wm * 64 + mi * 16 + r;
;             int col = nt * 128 + hc * 64 + ch * 4;
;             float* xo = p.out + grow * 1024 + col;
;             float4 xr = (MODE == 1 && layer == 0) ? *(const float4*)(xin_row(p, grow) + col) : *(const float4*)xo;
;             float4 xn = make_float4(xr.x + a4.x, xr.y + a4.y, xr.z + a4.z, xr.w + a4.w);
;             *(float4*)xo = xn;
	v_pk_add_f32 v[88:89], v[88:89], v[92:93]
	v_pk_add_f32 v[90:91], v[90:91], v[94:95]
	s_waitcnt vmcnt(8)
	s_nop 1
	v_mov_b32_e32 v92, v184
	v_mov_b32_e32 v93, v185
	v_mov_b32_e32 v94, v186
	v_mov_b32_e32 v95, v187
	s_nop 0
	global_store_dwordx4 v[106:107], v[88:91], off offset:256
	ds_read_b128 v[88:91], v172 offset:51328
	s_waitcnt lgkmcnt(0)
	v_pk_add_f32 v[88:89], v[88:89], v[92:93]
	v_pk_add_f32 v[90:91], v[90:91], v[94:95]
	s_waitcnt vmcnt(8)
	s_nop 1
	v_mov_b32_e32 v92, v188
	v_mov_b32_e32 v93, v189
	v_mov_b32_e32 v94, v190
	v_mov_b32_e32 v95, v191
	v_mov_b32_e32 v194, 0x20000
	v_mov_b32_e32 v195, 0
	v_lshl_add_u64 v[194:195], v[192:193], 0, v[194:195]
	global_load_dwordx4 v[0:3], v[194:195], off
	v_mov_b32_e32 v194, 0x24000
	v_mov_b32_e32 v195, 0
	v_lshl_add_u64 v[194:195], v[192:193], 0, v[194:195]
	global_load_dwordx4 v[4:7], v[194:195], off
	v_mov_b32_e32 v194, 0x28000
	v_mov_b32_e32 v195, 0
	v_lshl_add_u64 v[194:195], v[192:193], 0, v[194:195]
	global_load_dwordx4 v[8:11], v[194:195], off
	v_mov_b32_e32 v194, 0x2c000
	v_mov_b32_e32 v195, 0
	v_lshl_add_u64 v[194:195], v[192:193], 0, v[194:195]
	global_load_dwordx4 v[12:15], v[194:195], off
	v_mov_b32_e32 v194, 0x20000
	v_mov_b32_e32 v195, 0
	v_lshl_add_u64 v[194:195], v[192:193], 0, v[194:195]
	global_load_dwordx4 v[16:19], v[194:195], off offset:256
	v_mov_b32_e32 v194, 0x24000
	v_mov_b32_e32 v195, 0
	v_lshl_add_u64 v[194:195], v[192:193], 0, v[194:195]
	global_load_dwordx4 v[20:23], v[194:195], off offset:256
	v_mov_b32_e32 v194, 0x28000
	v_mov_b32_e32 v195, 0
	v_lshl_add_u64 v[194:195], v[192:193], 0, v[194:195]
	global_load_dwordx4 v[184:187], v[194:195], off offset:256
	v_mov_b32_e32 v194, 0x2c000
	v_mov_b32_e32 v195, 0
	v_lshl_add_u64 v[194:195], v[192:193], 0, v[194:195]
	global_load_dwordx4 v[188:191], v[194:195], off offset:256
	s_nop 0
	global_store_dwordx4 v[108:109], v[88:91], off offset:256
	ds_read_b128 v[88:91], v172 offset:52416
	s_waitcnt lgkmcnt(0)
	v_pk_add_f32 v[88:89], v[88:89], v[92:93]
	v_pk_add_f32 v[90:91], v[90:91], v[94:95]
	global_store_dwordx4 v[118:119], v[88:91], off offset:256
	ds_write2_b32 v175, v84, v80 offset1:16
	ds_write2_b32 v175, v76, v72 offset0:32 offset1:48
	ds_write2_b32 v175, v85, v81 offset0:68 offset1:84
	ds_write2_b32 v175, v77, v73 offset0:100 offset1:116
	ds_write2_b32 v175, v86, v82 offset0:136 offset1:152
	ds_write2_b32 v175, v78, v74 offset0:168 offset1:184
	ds_write2_b32 v175, v87, v83 offset0:204 offset1:220
	ds_write2_b32 v175, v79, v75 offset0:236 offset1:252
	v_or_b32_e32 v88, 32, v170
	v_or_b32_e32 v72, v88, v156
	v_mov_b32_e32 v73, v171
	v_lshlrev_b64 v[72:73], 12, v[72:73]
	v_lshl_add_u64 v[72:73], s[56:57], 0, v[72:73]
	v_lshl_add_u64 v[72:73], v[72:73], 0, v[136:137]
	s_waitcnt vmcnt(9)
	s_nop 1
	v_mov_b32_e32 v78, v0
	v_mov_b32_e32 v79, v1
	v_mov_b32_e32 v80, v2
	v_mov_b32_e32 v81, v3
	ds_read_b128 v[74:77], v172 offset:49152
	s_waitcnt lgkmcnt(0)
	v_pk_add_f32 v[74:75], v[74:75], v[78:79]
	v_pk_add_f32 v[76:77], v[76:77], v[80:81]
	global_store_dwordx4 v[72:73], v[74:77], off
	ds_read_b128 v[76:79], v172 offset:50240
	s_nop 0
	v_or_b32_e32 v74, v88, v160
	v_mov_b32_e32 v75, v171
	v_lshlrev_b64 v[74:75], 12, v[74:75]
	v_lshl_add_u64 v[74:75], s[56:57], 0, v[74:75]
	v_lshl_add_u64 v[74:75], v[74:75], 0, v[136:137]
	s_waitcnt vmcnt(9)
	s_nop 1
	v_mov_b32_e32 v80, v4
	v_mov_b32_e32 v81, v5
	v_mov_b32_e32 v82, v6
	v_mov_b32_e32 v83, v7
	s_waitcnt lgkmcnt(0)
	v_pk_add_f32 v[76:77], v[76:77], v[80:81]
	v_pk_add_f32 v[78:79], v[78:79], v[82:83]
	global_store_dwordx4 v[74:75], v[76:79], off
	ds_read_b128 v[78:81], v172 offset:51328
	s_nop 0
	v_or_b32_e32 v76, v88, v162
	v_mov_b32_e32 v77, v171
	v_lshlrev_b64 v[76:77], 12, v[76:77]
	v_lshl_add_u64 v[76:77], s[56:57], 0, v[76:77]
	v_lshl_add_u64 v[76:77], v[76:77], 0, v[136:137]
	s_waitcnt vmcnt(9)
	s_nop 1
	v_mov_b32_e32 v82, v8
	v_mov_b32_e32 v83, v9
	v_mov_b32_e32 v84, v10
	v_mov_b32_e32 v85, v11
	s_waitcnt lgkmcnt(0)
	v_pk_add_f32 v[78:79], v[78:79], v[82:83]
	v_pk_add_f32 v[80:81], v[80:81], v[84:85]
	global_store_dwordx4 v[76:77], v[78:81], off
	s_nop 1
	v_or_b32_e32 v78, v88, v164
	v_mov_b32_e32 v79, v171
	v_lshlrev_b64 v[78:79], 12, v[78:79]
	v_lshl_add_u64 v[78:79], s[56:57], 0, v[78:79]
	v_lshl_add_u64 v[86:87], v[78:79], 0, v[136:137]
	s_waitcnt vmcnt(9)
	s_nop 1
	v_mov_b32_e32 v82, v12
	v_mov_b32_e32 v83, v13
	v_mov_b32_e32 v84, v14
	v_mov_b32_e32 v85, v15
	ds_read_b128 v[78:81], v172 offset:52416
	s_waitcnt lgkmcnt(0)
	v_pk_add_f32 v[78:79], v[78:79], v[82:83]
	v_pk_add_f32 v[80:81], v[80:81], v[84:85]
	global_store_dwordx4 v[86:87], v[78:81], off
	ds_write2_b32 v175, v68, v64 offset1:16
	ds_write2_b32 v175, v60, v56 offset0:32 offset1:48
	ds_write2_b32 v175, v69, v65 offset0:68 offset1:84
	ds_write2_b32 v175, v61, v57 offset0:100 offset1:116
	ds_write2_b32 v175, v70, v66 offset0:136 offset1:152
	ds_write2_b32 v175, v62, v58 offset0:168 offset1:184
	ds_write2_b32 v175, v71, v67 offset0:204 offset1:220
	ds_write2_b32 v175, v63, v59 offset0:236 offset1:252
	s_waitcnt vmcnt(9)
	s_nop 1
	v_mov_b32_e32 v60, v16
	v_mov_b32_e32 v61, v17
	v_mov_b32_e32 v62, v18
	v_mov_b32_e32 v63, v19
	ds_read_b128 v[56:59], v172 offset:49152
	s_waitcnt lgkmcnt(0)
	v_pk_add_f32 v[56:57], v[56:57], v[60:61]
	v_pk_add_f32 v[58:59], v[58:59], v[62:63]
	s_waitcnt vmcnt(8)
	s_nop 1
	v_mov_b32_e32 v60, v20
	v_mov_b32_e32 v61, v21
	v_mov_b32_e32 v62, v22
	v_mov_b32_e32 v63, v23
	s_nop 0
	global_store_dwordx4 v[72:73], v[56:59], off offset:256
	ds_read_b128 v[56:59], v172 offset:50240
	s_waitcnt lgkmcnt(0)
	v_pk_add_f32 v[56:57], v[56:57], v[60:61]
	v_pk_add_f32 v[58:59], v[58:59], v[62:63]
	s_waitcnt vmcnt(8)
; template <int MODE, int HALF>
; __device__ void gemm_phase(const P& p, int layer, char* smem) {
;     ...
;         for (int hc = 0; hc < 2; ++hc) {
; #pragma unroll
;           for (int j = 0; j < 4; ++j)
; #pragma unroll
;             for (int n4 = 0; n4 < 4; ++n4) pf[(lqe * 4 + j) * 68 + n4 * 16 + lre] = acc[mi][hc * 4 + n4][j];
;           asm volatile("" ::: "memory");
; #pragma unroll
;           for (int it = 0; it < 4; ++it) {
;             int idx = it * 64 + lane, r = idx >> 4, ch = idx & 15;
;             float4 a4 = *(const float4*)(pf + r * 68 + ch * 4);
;             size_t grow = row0 + wm * 64 + mi * 16 + r;
;             int col = nt * 128 + hc * 64 + ch * 4;
;             float* xo = p.out + grow * 1024 + col;
;             float4 xr = (MODE == 1 && layer == 0) ? *(const float4*)(xin_row(p, grow) + col) : *(const float4*)xo;
;             float4 xn = make_float4(xr.x + a4.x, xr.y + a4.y, xr.z + a4.z, xr.w + a4.w);
;             *(float4*)xo = xn;
;     ...
;     if (t_next >= total) break;
;     t = t_next;
	s_nop 1
	v_mov_b32_e32 v60, v184
	v_mov_b32_e32 v61, v185
	v_mov_b32_e32 v62, v186
	v_mov_b32_e32 v63, v187
	s_nop 0
	global_store_dwordx4 v[74:75], v[56:59], off offset:256
	ds_read_b128 v[56:59], v172 offset:51328
	s_waitcnt lgkmcnt(0)
	v_pk_add_f32 v[56:57], v[56:57], v[60:61]
	v_pk_add_f32 v[58:59], v[58:59], v[62:63]
	s_waitcnt vmcnt(8)
	s_nop 1
	v_mov_b32_e32 v60, v188
	v_mov_b32_e32 v61, v189
	v_mov_b32_e32 v62, v190
	v_mov_b32_e32 v63, v191
	v_mov_b32_e32 v194, 0x30000
	v_mov_b32_e32 v195, 0
	v_lshl_add_u64 v[194:195], v[192:193], 0, v[194:195]
	global_load_dwordx4 v[0:3], v[194:195], off
	v_mov_b32_e32 v194, 0x34000
	v_mov_b32_e32 v195, 0
	v_lshl_add_u64 v[194:195], v[192:193], 0, v[194:195]
	global_load_dwordx4 v[4:7], v[194:195], off
	v_mov_b32_e32 v194, 0x38000
	v_mov_b32_e32 v195, 0
	v_lshl_add_u64 v[194:195], v[192:193], 0, v[194:195]
	global_load_dwordx4 v[8:11], v[194:195], off
	v_mov_b32_e32 v194, 0x3c000
	v_mov_b32_e32 v195, 0
	v_lshl_add_u64 v[194:195], v[192:193], 0, v[194:195]
	global_load_dwordx4 v[12:15], v[194:195], off
	v_mov_b32_e32 v194, 0x30000
	v_mov_b32_e32 v195, 0
	v_lshl_add_u64 v[194:195], v[192:193], 0, v[194:195]
	global_load_dwordx4 v[16:19], v[194:195], off offset:256
	v_mov_b32_e32 v194, 0x34000
	v_mov_b32_e32 v195, 0
	v_lshl_add_u64 v[194:195], v[192:193], 0, v[194:195]
	global_load_dwordx4 v[20:23], v[194:195], off offset:256
	v_mov_b32_e32 v194, 0x38000
	v_mov_b32_e32 v195, 0
	v_lshl_add_u64 v[194:195], v[192:193], 0, v[194:195]
	global_load_dwordx4 v[184:187], v[194:195], off offset:256
	v_mov_b32_e32 v194, 0x3c000
	v_mov_b32_e32 v195, 0
	v_lshl_add_u64 v[194:195], v[192:193], 0, v[194:195]
	global_load_dwordx4 v[188:191], v[194:195], off offset:256
	s_nop 0
	global_store_dwordx4 v[76:77], v[56:59], off offset:256
	ds_read_b128 v[56:59], v172 offset:52416
	s_waitcnt lgkmcnt(0)
	v_pk_add_f32 v[56:57], v[56:57], v[60:61]
	v_pk_add_f32 v[58:59], v[58:59], v[62:63]
	global_store_dwordx4 v[86:87], v[56:59], off offset:256
	ds_write2_b32 v175, v52, v48 offset1:16
	ds_write2_b32 v175, v44, v40 offset0:32 offset1:48
	ds_write2_b32 v175, v53, v49 offset0:68 offset1:84
	ds_write2_b32 v175, v45, v41 offset0:100 offset1:116
	ds_write2_b32 v175, v54, v50 offset0:136 offset1:152
	ds_write2_b32 v175, v46, v42 offset0:168 offset1:184
	ds_write2_b32 v175, v55, v51 offset0:204 offset1:220
	ds_write2_b32 v175, v47, v43 offset0:236 offset1:252
	v_or_b32_e32 v56, 48, v170
	v_or_b32_e32 v170, v56, v156
	v_lshlrev_b64 v[40:41], 12, v[170:171]
	v_lshl_add_u64 v[40:41], s[56:57], 0, v[40:41]
	v_lshl_add_u64 v[40:41], v[40:41], 0, v[136:137]
	s_waitcnt vmcnt(9)
	s_nop 1
	v_mov_b32_e32 v46, v0
	v_mov_b32_e32 v47, v1
	v_mov_b32_e32 v48, v2
	v_mov_b32_e32 v49, v3
	ds_read_b128 v[42:45], v172 offset:49152
	v_or_b32_e32 v170, v56, v160
	s_waitcnt lgkmcnt(0)
	v_pk_add_f32 v[42:43], v[42:43], v[46:47]
	v_pk_add_f32 v[44:45], v[44:45], v[48:49]
	global_store_dwordx4 v[40:41], v[42:45], off
	ds_read_b128 v[44:47], v172 offset:50240
	s_nop 0
	v_lshlrev_b64 v[42:43], 12, v[170:171]
	v_lshl_add_u64 v[42:43], s[56:57], 0, v[42:43]
	v_lshl_add_u64 v[42:43], v[42:43], 0, v[136:137]
	s_waitcnt vmcnt(9)
	s_nop 1
	v_mov_b32_e32 v48, v4
	v_mov_b32_e32 v49, v5
	v_mov_b32_e32 v50, v6
	v_mov_b32_e32 v51, v7
	v_or_b32_e32 v170, v56, v162
	s_waitcnt lgkmcnt(0)
	v_pk_add_f32 v[44:45], v[44:45], v[48:49]
	v_pk_add_f32 v[46:47], v[46:47], v[50:51]
	global_store_dwordx4 v[42:43], v[44:47], off
	ds_read_b128 v[46:49], v172 offset:51328
	s_nop 0
	v_lshlrev_b64 v[44:45], 12, v[170:171]
	v_lshl_add_u64 v[44:45], s[56:57], 0, v[44:45]
	v_lshl_add_u64 v[44:45], v[44:45], 0, v[136:137]
	s_waitcnt vmcnt(9)
	s_nop 1
	v_mov_b32_e32 v50, v8
	v_mov_b32_e32 v51, v9
	v_mov_b32_e32 v52, v10
	v_mov_b32_e32 v53, v11
	v_or_b32_e32 v170, v56, v164
	s_waitcnt lgkmcnt(0)
	v_pk_add_f32 v[46:47], v[46:47], v[50:51]
	v_pk_add_f32 v[48:49], v[48:49], v[52:53]
	global_store_dwordx4 v[44:45], v[46:49], off
	s_nop 1
	v_lshlrev_b64 v[46:47], 12, v[170:171]
	v_lshl_add_u64 v[46:47], s[56:57], 0, v[46:47]
	v_lshl_add_u64 v[54:55], v[46:47], 0, v[136:137]
	s_waitcnt vmcnt(9)
	s_nop 1
	v_mov_b32_e32 v50, v12
	v_mov_b32_e32 v51, v13
	v_mov_b32_e32 v52, v14
	v_mov_b32_e32 v53, v15
	ds_read_b128 v[46:49], v172 offset:52416
	s_waitcnt lgkmcnt(0)
	v_pk_add_f32 v[46:47], v[46:47], v[50:51]
	v_pk_add_f32 v[48:49], v[48:49], v[52:53]
	global_store_dwordx4 v[54:55], v[46:49], off
	ds_write2_b32 v175, v24, v28 offset1:16
	ds_write2_b32 v175, v32, v36 offset0:32 offset1:48
	ds_write2_b32 v175, v25, v29 offset0:68 offset1:84
	ds_write2_b32 v175, v33, v37 offset0:100 offset1:116
	ds_write2_b32 v175, v26, v30 offset0:136 offset1:152
	ds_write2_b32 v175, v34, v38 offset0:168 offset1:184
	ds_write2_b32 v175, v27, v31 offset0:204 offset1:220
	ds_write2_b32 v175, v35, v39 offset0:236 offset1:252
	s_waitcnt vmcnt(9)
	s_nop 1
	v_mov_b32_e32 v28, v16
	v_mov_b32_e32 v29, v17
	v_mov_b32_e32 v30, v18
	v_mov_b32_e32 v31, v19
	ds_read_b128 v[24:27], v172 offset:49152
	s_waitcnt lgkmcnt(0)
	v_pk_add_f32 v[24:25], v[24:25], v[28:29]
	v_pk_add_f32 v[26:27], v[26:27], v[30:31]
	s_waitcnt vmcnt(8)
	s_nop 1
	v_mov_b32_e32 v28, v20
	v_mov_b32_e32 v29, v21
	v_mov_b32_e32 v30, v22
	v_mov_b32_e32 v31, v23
	s_nop 0
	global_store_dwordx4 v[40:41], v[24:27], off offset:256
	ds_read_b128 v[24:27], v172 offset:50240
	s_waitcnt lgkmcnt(0)
	v_pk_add_f32 v[24:25], v[24:25], v[28:29]
	v_pk_add_f32 v[26:27], v[26:27], v[30:31]
	s_waitcnt vmcnt(8)
	s_nop 1
	v_mov_b32_e32 v28, v184
	v_mov_b32_e32 v29, v185
	v_mov_b32_e32 v30, v186
	v_mov_b32_e32 v31, v187
	s_nop 0
	global_store_dwordx4 v[42:43], v[24:27], off offset:256
	ds_read_b128 v[24:27], v172 offset:51328
	s_waitcnt lgkmcnt(0)
	v_pk_add_f32 v[24:25], v[24:25], v[28:29]
	v_pk_add_f32 v[26:27], v[26:27], v[30:31]
	s_waitcnt vmcnt(8)
	s_nop 1
	v_mov_b32_e32 v28, v188
	v_mov_b32_e32 v29, v189
	v_mov_b32_e32 v30, v190
	v_mov_b32_e32 v31, v191
	s_nop 0
	global_store_dwordx4 v[44:45], v[24:27], off offset:256
	ds_read_b128 v[24:27], v172 offset:52416
	s_waitcnt lgkmcnt(0)
	v_pk_add_f32 v[24:25], v[24:25], v[28:29]
	v_pk_add_f32 v[26:27], v[26:27], v[30:31]
	global_store_dwordx4 v[54:55], v[24:27], off offset:256
	s_cbranch_scc1 .LBB0_182
